# optimistic fast softmax: no max chain on the fast path, row-sum overflow check and per-tile redo
# baseline (speedup 1.0000x reference)
.Lattn_loop_f:
	s_waitcnt vmcnt(4)
	s_barrier
	s_waitcnt lgkmcnt(5)
	v_mfma_f32_32x32x16_bf16 v[48:63], v[216:219], v[144:147], v[48:63]
	ds_read_b128 v[216:219], v188 offset:8192
	s_add_i32 s2, s42, 3
	s_and_b32 s2, s2, 31
	s_mul_i32 s2, s2, 0x44000
	s_add_i32 m0, s5, 0
	s_add_u32 s40, s26, s2
	s_addc_u32 s41, s27, 0
	global_load_lds_dwordx4 v170, s[40:41]
	s_add_i32 m0, s5, 8192
	s_waitcnt lgkmcnt(5)
	v_mfma_f32_32x32x16_bf16 v[32:47], v[220:223], v[144:147], v[32:47]
	ds_read_b128 v[220:223], v188 offset:12288
	s_add_u32 s40, s40, 0x80
	s_addc_u32 s41, s41, 0
	global_load_lds_dwordx4 v170, s[40:41]
	s_add_i32 s2, s42, 2
	s_and_b32 s2, s2, 31
	s_lshl_b32 s2, s2, 7
	s_add_i32 m0, s5, 114688
	s_add_u32 s44, s10, s2
	s_waitcnt lgkmcnt(5)
	v_mfma_f32_32x32x16_bf16 v[16:31], v[224:227], v[144:147], v[16:31]
	ds_read_b128 v[224:227], v186 offset:0
	s_addc_u32 s45, s11, 0
	global_load_lds_dwordx4 v172, s[44:45]
	s_add_i32 m0, s5, 122880
	s_add_u32 s44, s44, 0x204000
	s_addc_u32 s45, s45, 0
	global_load_lds_dwordx4 v172, s[44:45]
	s_waitcnt lgkmcnt(5)
	v_mfma_f32_32x32x16_bf16 v[0:15], v[228:231], v[144:147], v[0:15]
	ds_read_b128 v[228:231], v186 offset:4096
	v_exp_f32_e32 v171, v96
	v_exp_f32_e32 v173, v97
	v_exp_f32_e32 v179, v98
	v_exp_f32_e32 v180, v99
	s_waitcnt lgkmcnt(5)
	v_mfma_f32_32x32x16_bf16 v[48:63], v[208:211], v[148:151], v[48:63]
	ds_read_b128 v[208:211], v186 offset:8192
	v_exp_f32_e32 v232, v100
	v_exp_f32_e32 v233, v101
	v_exp_f32_e32 v234, v102
	v_exp_f32_e32 v235, v103
	s_waitcnt lgkmcnt(5)
	v_mfma_f32_32x32x16_bf16 v[32:47], v[212:215], v[148:151], v[32:47]
	ds_read_b128 v[212:215], v186 offset:12288
	v_add_f32_e32 v190, v171, v173
	v_add_f32_e32 v191, v179, v180
	v_add_f32_e32 v190, v190, v232
	v_add_f32_e32 v191, v191, v233
	s_waitcnt lgkmcnt(5)
	v_mfma_f32_32x32x16_bf16 v[16:31], v[216:219], v[148:151], v[16:31]
	ds_read_b128 v[216:219], v189 offset:0
	v_add_f32_e32 v190, v190, v234
	v_add_f32_e32 v191, v191, v235
	v_cvt_pk_bf16_f32 v144, v171, v173
	v_cvt_pk_bf16_f32 v145, v179, v180
	s_waitcnt lgkmcnt(5)
	v_mfma_f32_32x32x16_bf16 v[0:15], v[220:223], v[148:151], v[0:15]
	ds_read_b128 v[220:223], v189 offset:4096
	v_cvt_pk_bf16_f32 v146, v232, v233
	v_cvt_pk_bf16_f32 v147, v234, v235
	v_exp_f32_e32 v171, v104
	v_exp_f32_e32 v173, v105
	s_waitcnt lgkmcnt(5)
	v_mfma_f32_32x32x16_bf16 v[48:63], v[224:227], v[152:155], v[48:63]
	ds_read_b128 v[224:227], v189 offset:8192
	v_exp_f32_e32 v179, v106
	v_exp_f32_e32 v180, v107
	v_exp_f32_e32 v232, v108
	v_exp_f32_e32 v233, v109
	s_waitcnt lgkmcnt(5)
	v_mfma_f32_32x32x16_bf16 v[32:47], v[228:231], v[152:155], v[32:47]
	ds_read_b128 v[228:231], v189 offset:12288
	v_exp_f32_e32 v234, v110
	v_exp_f32_e32 v235, v111
	v_add_f32_e32 v190, v190, v171
	v_add_f32_e32 v191, v191, v173
	s_waitcnt lgkmcnt(5)
	v_mfma_f32_32x32x16_bf16 v[16:31], v[208:211], v[152:155], v[16:31]
	ds_read_b128 v[208:211], v182 offset:32768
	v_add_f32_e32 v190, v190, v179
	v_add_f32_e32 v191, v191, v180
	v_add_f32_e32 v190, v190, v232
	v_add_f32_e32 v191, v191, v233
	s_waitcnt lgkmcnt(5)
	v_mfma_f32_32x32x16_bf16 v[0:15], v[212:215], v[152:155], v[0:15]
	ds_read_b128 v[212:215], v182 offset:36864
	v_add_f32_e32 v190, v190, v234
	v_add_f32_e32 v191, v191, v235
	v_cvt_pk_bf16_f32 v148, v171, v173
	v_cvt_pk_bf16_f32 v149, v179, v180
	s_waitcnt lgkmcnt(5)
	v_mfma_f32_32x32x16_bf16 v[48:63], v[216:219], v[156:159], v[48:63]
	ds_read_b128 v[216:219], v183 offset:32768
	v_cvt_pk_bf16_f32 v150, v232, v233
	v_cvt_pk_bf16_f32 v151, v234, v235
	v_exp_f32_e32 v171, v112
	v_exp_f32_e32 v173, v113
	s_waitcnt lgkmcnt(5)
	v_mfma_f32_32x32x16_bf16 v[32:47], v[220:223], v[156:159], v[32:47]
	ds_read_b128 v[220:223], v183 offset:36864
	v_exp_f32_e32 v179, v114
	v_exp_f32_e32 v180, v115
	v_exp_f32_e32 v232, v116
	v_exp_f32_e32 v233, v117
	s_waitcnt lgkmcnt(5)
	v_mfma_f32_32x32x16_bf16 v[16:31], v[224:227], v[156:159], v[16:31]
	ds_read_b128 v[224:227], v184 offset:32768
	v_exp_f32_e32 v234, v118
	v_exp_f32_e32 v235, v119
	v_add_f32_e32 v190, v190, v171
	v_add_f32_e32 v191, v191, v173
	s_waitcnt lgkmcnt(5)
	v_mfma_f32_32x32x16_bf16 v[0:15], v[228:231], v[156:159], v[0:15]
	ds_read_b128 v[228:231], v184 offset:36864
	v_add_f32_e32 v190, v190, v179
	v_add_f32_e32 v191, v191, v180
	v_add_f32_e32 v190, v190, v232
	v_add_f32_e32 v191, v191, v233
	s_waitcnt lgkmcnt(5)
	v_mfma_f32_32x32x16_bf16 v[64:79], v[208:211], v[128:131], 0
	ds_read_b128 v[208:211], v185 offset:32768
	v_add_f32_e32 v190, v190, v234
	v_add_f32_e32 v191, v191, v235
	v_cvt_pk_bf16_f32 v152, v171, v173
	v_cvt_pk_bf16_f32 v153, v179, v180
	s_waitcnt lgkmcnt(5)
	v_mfma_f32_32x32x16_bf16 v[80:95], v[212:215], v[128:131], 0
	ds_read_b128 v[212:215], v185 offset:36864
	v_cvt_pk_bf16_f32 v154, v232, v233
	v_cvt_pk_bf16_f32 v155, v234, v235
	v_exp_f32_e32 v171, v120
	v_exp_f32_e32 v173, v121
	s_waitcnt lgkmcnt(5)
	v_mfma_f32_32x32x16_bf16 v[64:79], v[216:219], v[132:135], v[64:79]
	ds_read_b128 v[216:219], v187 offset:16384
	v_exp_f32_e32 v179, v122
	v_exp_f32_e32 v180, v123
	v_exp_f32_e32 v232, v124
	v_exp_f32_e32 v233, v125
	s_waitcnt lgkmcnt(5)
	v_mfma_f32_32x32x16_bf16 v[80:95], v[220:223], v[132:135], v[80:95]
	ds_read_b128 v[220:223], v187 offset:20480
	v_exp_f32_e32 v234, v126
	v_exp_f32_e32 v235, v127
	v_add_f32_e32 v190, v190, v171
	s_waitcnt lgkmcnt(5)
	v_mfma_f32_32x32x16_bf16 v[64:79], v[224:227], v[136:139], v[64:79]
	ds_read_b128 v[224:227], v187 offset:24576
	v_add_f32_e32 v191, v191, v173
	v_add_f32_e32 v190, v190, v179
	v_add_f32_e32 v191, v191, v180
	s_waitcnt lgkmcnt(5)
	v_mfma_f32_32x32x16_bf16 v[80:95], v[228:231], v[136:139], v[80:95]
	ds_read_b128 v[228:231], v187 offset:28672
	v_add_f32_e32 v190, v190, v232
	v_add_f32_e32 v191, v191, v233
	v_add_f32_e32 v190, v190, v234
	s_waitcnt lgkmcnt(5)
	v_mfma_f32_32x32x16_bf16 v[64:79], v[208:211], v[140:143], v[64:79]
	ds_read_b128 v[208:211], v188 offset:16384
	v_add_f32_e32 v191, v191, v235
	v_cvt_pk_bf16_f32 v156, v171, v173
	v_cvt_pk_bf16_f32 v157, v179, v180
	s_waitcnt lgkmcnt(5)
	v_mfma_f32_32x32x16_bf16 v[80:95], v[212:215], v[140:143], v[80:95]
	ds_read_b128 v[212:215], v188 offset:20480
	v_cvt_pk_bf16_f32 v158, v232, v233
	v_cvt_pk_bf16_f32 v159, v234, v235
	v_add_f32_e32 v190, v190, v191
	v_cmp_ngt_f32_e32 vcc, 0x71800000, v190
	s_nop 4
	s_cbranch_vccnz .Lattn_redo_L0
	v_add_f32_e32 v167, v167, v190
	s_waitcnt vmcnt(4)
	s_barrier
	s_waitcnt lgkmcnt(5)
	v_mfma_f32_32x32x16_bf16 v[48:63], v[216:219], v[144:147], v[48:63]
	ds_read_b128 v[216:219], v188 offset:24576
	s_add_i32 s2, s42, 4
	s_and_b32 s2, s2, 31
	s_mul_i32 s2, s2, 0x44000
	s_add_i32 m0, s5, 16384
	s_add_u32 s40, s26, s2
	s_addc_u32 s41, s27, 0
	global_load_lds_dwordx4 v170, s[40:41]
	s_add_i32 m0, s5, 24576
	s_waitcnt lgkmcnt(5)
	v_mfma_f32_32x32x16_bf16 v[32:47], v[220:223], v[144:147], v[32:47]
	ds_read_b128 v[220:223], v188 offset:28672
	s_add_u32 s40, s40, 0x80
	s_addc_u32 s41, s41, 0
	global_load_lds_dwordx4 v170, s[40:41]
	s_add_i32 s2, s42, 3
	s_and_b32 s2, s2, 31
	s_lshl_b32 s2, s2, 7
	s_add_i32 m0, s5, 65536
	s_add_u32 s44, s10, s2
	s_waitcnt lgkmcnt(5)
	v_mfma_f32_32x32x16_bf16 v[16:31], v[224:227], v[144:147], v[16:31]
	ds_read_b128 v[224:227], v186 offset:16384
	s_addc_u32 s45, s11, 0
	global_load_lds_dwordx4 v172, s[44:45]
	s_add_i32 m0, s5, 73728
	s_add_u32 s44, s44, 0x204000
	s_addc_u32 s45, s45, 0
	global_load_lds_dwordx4 v172, s[44:45]
	s_waitcnt lgkmcnt(5)
	v_mfma_f32_32x32x16_bf16 v[0:15], v[228:231], v[144:147], v[0:15]
	ds_read_b128 v[228:231], v186 offset:20480
	v_exp_f32_e32 v171, v64
	v_exp_f32_e32 v173, v65
	v_exp_f32_e32 v179, v66
	v_exp_f32_e32 v180, v67
	s_waitcnt lgkmcnt(5)
	v_mfma_f32_32x32x16_bf16 v[48:63], v[208:211], v[148:151], v[48:63]
	ds_read_b128 v[208:211], v186 offset:24576
	v_exp_f32_e32 v232, v68
	v_exp_f32_e32 v233, v69
	v_exp_f32_e32 v234, v70
	v_exp_f32_e32 v235, v71
	s_waitcnt lgkmcnt(5)
	v_mfma_f32_32x32x16_bf16 v[32:47], v[212:215], v[148:151], v[32:47]
	ds_read_b128 v[212:215], v186 offset:28672
	v_add_f32_e32 v190, v171, v173
	v_add_f32_e32 v191, v179, v180
	v_add_f32_e32 v190, v190, v232
	v_add_f32_e32 v191, v191, v233
	s_waitcnt lgkmcnt(5)
	v_mfma_f32_32x32x16_bf16 v[16:31], v[216:219], v[148:151], v[16:31]
	ds_read_b128 v[216:219], v189 offset:16384
	v_add_f32_e32 v190, v190, v234
	v_add_f32_e32 v191, v191, v235
	v_cvt_pk_bf16_f32 v144, v171, v173
	v_cvt_pk_bf16_f32 v145, v179, v180
	s_waitcnt lgkmcnt(5)
	v_mfma_f32_32x32x16_bf16 v[0:15], v[220:223], v[148:151], v[0:15]
	ds_read_b128 v[220:223], v189 offset:20480
	v_cvt_pk_bf16_f32 v146, v232, v233
	v_cvt_pk_bf16_f32 v147, v234, v235
	v_exp_f32_e32 v171, v72
	v_exp_f32_e32 v173, v73
	s_waitcnt lgkmcnt(5)
	v_mfma_f32_32x32x16_bf16 v[48:63], v[224:227], v[152:155], v[48:63]
	ds_read_b128 v[224:227], v189 offset:24576
	v_exp_f32_e32 v179, v74
	v_exp_f32_e32 v180, v75
	v_exp_f32_e32 v232, v76
	v_exp_f32_e32 v233, v77
	s_waitcnt lgkmcnt(5)
	v_mfma_f32_32x32x16_bf16 v[32:47], v[228:231], v[152:155], v[32:47]
	ds_read_b128 v[228:231], v189 offset:28672
	v_exp_f32_e32 v234, v78
	v_exp_f32_e32 v235, v79
	v_add_f32_e32 v190, v190, v171
	v_add_f32_e32 v191, v191, v173
	s_waitcnt lgkmcnt(5)
	v_mfma_f32_32x32x16_bf16 v[16:31], v[208:211], v[152:155], v[16:31]
	ds_read_b128 v[208:211], v182 offset:49152
	v_add_f32_e32 v190, v190, v179
	v_add_f32_e32 v191, v191, v180
	v_add_f32_e32 v190, v190, v232
	v_add_f32_e32 v191, v191, v233
	s_waitcnt lgkmcnt(5)
	v_mfma_f32_32x32x16_bf16 v[0:15], v[212:215], v[152:155], v[0:15]
	ds_read_b128 v[212:215], v182 offset:53248
	v_add_f32_e32 v190, v190, v234
	v_add_f32_e32 v191, v191, v235
	v_cvt_pk_bf16_f32 v148, v171, v173
	v_cvt_pk_bf16_f32 v149, v179, v180
	s_waitcnt lgkmcnt(5)
	v_mfma_f32_32x32x16_bf16 v[48:63], v[216:219], v[156:159], v[48:63]
	ds_read_b128 v[216:219], v183 offset:49152
	v_cvt_pk_bf16_f32 v150, v232, v233
	v_cvt_pk_bf16_f32 v151, v234, v235
	v_exp_f32_e32 v171, v80
	v_exp_f32_e32 v173, v81
	s_waitcnt lgkmcnt(5)
	v_mfma_f32_32x32x16_bf16 v[32:47], v[220:223], v[156:159], v[32:47]
	ds_read_b128 v[220:223], v183 offset:53248
	v_exp_f32_e32 v179, v82
	v_exp_f32_e32 v180, v83
	v_exp_f32_e32 v232, v84
	v_exp_f32_e32 v233, v85
	s_waitcnt lgkmcnt(5)
	v_mfma_f32_32x32x16_bf16 v[16:31], v[224:227], v[156:159], v[16:31]
	ds_read_b128 v[224:227], v184 offset:49152
	v_exp_f32_e32 v234, v86
	v_exp_f32_e32 v235, v87
	v_add_f32_e32 v190, v190, v171
	v_add_f32_e32 v191, v191, v173
	s_waitcnt lgkmcnt(5)
	v_mfma_f32_32x32x16_bf16 v[0:15], v[228:231], v[156:159], v[0:15]
	ds_read_b128 v[228:231], v184 offset:53248
	v_add_f32_e32 v190, v190, v179
	v_add_f32_e32 v191, v191, v180
	v_add_f32_e32 v190, v190, v232
	v_add_f32_e32 v191, v191, v233
	s_waitcnt lgkmcnt(5)
	v_mfma_f32_32x32x16_bf16 v[96:111], v[208:211], v[128:131], 0
	ds_read_b128 v[208:211], v185 offset:49152
	v_add_f32_e32 v190, v190, v234
	v_add_f32_e32 v191, v191, v235
	v_cvt_pk_bf16_f32 v152, v171, v173
	v_cvt_pk_bf16_f32 v153, v179, v180
	s_waitcnt lgkmcnt(5)
	v_mfma_f32_32x32x16_bf16 v[112:127], v[212:215], v[128:131], 0
	ds_read_b128 v[212:215], v185 offset:53248
	v_cvt_pk_bf16_f32 v154, v232, v233
	v_cvt_pk_bf16_f32 v155, v234, v235
	v_exp_f32_e32 v171, v88
	v_exp_f32_e32 v173, v89
	s_waitcnt lgkmcnt(5)
	v_mfma_f32_32x32x16_bf16 v[96:111], v[216:219], v[132:135], v[96:111]
	ds_read_b128 v[216:219], v187 offset:32768
	v_exp_f32_e32 v179, v90
	v_exp_f32_e32 v180, v91
	v_exp_f32_e32 v232, v92
	v_exp_f32_e32 v233, v93
	s_waitcnt lgkmcnt(5)
	v_mfma_f32_32x32x16_bf16 v[112:127], v[220:223], v[132:135], v[112:127]
	ds_read_b128 v[220:223], v187 offset:36864
	v_exp_f32_e32 v234, v94
	v_exp_f32_e32 v235, v95
	v_add_f32_e32 v190, v190, v171
	s_waitcnt lgkmcnt(5)
	v_mfma_f32_32x32x16_bf16 v[96:111], v[224:227], v[136:139], v[96:111]
	ds_read_b128 v[224:227], v187 offset:40960
	v_add_f32_e32 v191, v191, v173
	v_add_f32_e32 v190, v190, v179
	v_add_f32_e32 v191, v191, v180
	s_waitcnt lgkmcnt(5)
	v_mfma_f32_32x32x16_bf16 v[112:127], v[228:231], v[136:139], v[112:127]
	ds_read_b128 v[228:231], v187 offset:45056
	v_add_f32_e32 v190, v190, v232
	v_add_f32_e32 v191, v191, v233
	v_add_f32_e32 v190, v190, v234
	s_waitcnt lgkmcnt(5)
	v_mfma_f32_32x32x16_bf16 v[96:111], v[208:211], v[140:143], v[96:111]
	ds_read_b128 v[208:211], v188 offset:32768
	v_add_f32_e32 v191, v191, v235
	v_cvt_pk_bf16_f32 v156, v171, v173
	v_cvt_pk_bf16_f32 v157, v179, v180
	s_waitcnt lgkmcnt(5)
	v_mfma_f32_32x32x16_bf16 v[112:127], v[212:215], v[140:143], v[112:127]
	ds_read_b128 v[212:215], v188 offset:36864
	v_cvt_pk_bf16_f32 v158, v232, v233
	v_cvt_pk_bf16_f32 v159, v234, v235
	v_add_f32_e32 v190, v190, v191
	v_cmp_ngt_f32_e32 vcc, 0x71800000, v190
	s_nop 4
	s_cbranch_vccnz .Lattn_redo_L1
	v_add_f32_e32 v167, v167, v190
	s_waitcnt vmcnt(4)
	s_barrier
	s_waitcnt lgkmcnt(5)
	v_mfma_f32_32x32x16_bf16 v[48:63], v[216:219], v[144:147], v[48:63]
	ds_read_b128 v[216:219], v188 offset:40960
	s_add_i32 s2, s42, 5
	s_and_b32 s2, s2, 31
	s_mul_i32 s2, s2, 0x44000
	s_add_i32 m0, s5, 32768
	s_add_u32 s40, s26, s2
	s_addc_u32 s41, s27, 0
	global_load_lds_dwordx4 v170, s[40:41]
	s_add_i32 m0, s5, 40960
	s_waitcnt lgkmcnt(5)
	v_mfma_f32_32x32x16_bf16 v[32:47], v[220:223], v[144:147], v[32:47]
	ds_read_b128 v[220:223], v188 offset:45056
	s_add_u32 s40, s40, 0x80
	s_addc_u32 s41, s41, 0
	global_load_lds_dwordx4 v170, s[40:41]
	s_add_i32 s2, s42, 4
	s_and_b32 s2, s2, 31
	s_lshl_b32 s2, s2, 7
	s_add_i32 m0, s5, 81920
	s_add_u32 s44, s10, s2
	s_waitcnt lgkmcnt(5)
	v_mfma_f32_32x32x16_bf16 v[16:31], v[224:227], v[144:147], v[16:31]
	ds_read_b128 v[224:227], v186 offset:32768
	s_addc_u32 s45, s11, 0
	global_load_lds_dwordx4 v172, s[44:45]
	s_add_i32 m0, s5, 90112
	s_add_u32 s44, s44, 0x204000
	s_addc_u32 s45, s45, 0
	global_load_lds_dwordx4 v172, s[44:45]
	s_waitcnt lgkmcnt(5)
	v_mfma_f32_32x32x16_bf16 v[0:15], v[228:231], v[144:147], v[0:15]
	ds_read_b128 v[228:231], v186 offset:36864
	v_exp_f32_e32 v171, v96
	v_exp_f32_e32 v173, v97
	v_exp_f32_e32 v179, v98
	v_exp_f32_e32 v180, v99
	s_waitcnt lgkmcnt(5)
	v_mfma_f32_32x32x16_bf16 v[48:63], v[208:211], v[148:151], v[48:63]
	ds_read_b128 v[208:211], v186 offset:40960
	v_exp_f32_e32 v232, v100
	v_exp_f32_e32 v233, v101
	v_exp_f32_e32 v234, v102
	v_exp_f32_e32 v235, v103
	s_waitcnt lgkmcnt(5)
	v_mfma_f32_32x32x16_bf16 v[32:47], v[212:215], v[148:151], v[32:47]
	ds_read_b128 v[212:215], v186 offset:45056
	v_add_f32_e32 v190, v171, v173
	v_add_f32_e32 v191, v179, v180
	v_add_f32_e32 v190, v190, v232
	v_add_f32_e32 v191, v191, v233
	s_waitcnt lgkmcnt(5)
	v_mfma_f32_32x32x16_bf16 v[16:31], v[216:219], v[148:151], v[16:31]
	ds_read_b128 v[216:219], v189 offset:32768
	v_add_f32_e32 v190, v190, v234
	v_add_f32_e32 v191, v191, v235
	v_cvt_pk_bf16_f32 v144, v171, v173
	v_cvt_pk_bf16_f32 v145, v179, v180
	s_waitcnt lgkmcnt(5)
	v_mfma_f32_32x32x16_bf16 v[0:15], v[220:223], v[148:151], v[0:15]
	ds_read_b128 v[220:223], v189 offset:36864
	v_cvt_pk_bf16_f32 v146, v232, v233
	v_cvt_pk_bf16_f32 v147, v234, v235
	v_exp_f32_e32 v171, v104
	v_exp_f32_e32 v173, v105
	s_waitcnt lgkmcnt(5)
	v_mfma_f32_32x32x16_bf16 v[48:63], v[224:227], v[152:155], v[48:63]
	ds_read_b128 v[224:227], v189 offset:40960
	v_exp_f32_e32 v179, v106
	v_exp_f32_e32 v180, v107
	v_exp_f32_e32 v232, v108
	v_exp_f32_e32 v233, v109
	s_waitcnt lgkmcnt(5)
	v_mfma_f32_32x32x16_bf16 v[32:47], v[228:231], v[152:155], v[32:47]
	ds_read_b128 v[228:231], v189 offset:45056
	v_exp_f32_e32 v234, v110
	v_exp_f32_e32 v235, v111
	v_add_f32_e32 v190, v190, v171
	v_add_f32_e32 v191, v191, v173
	s_waitcnt lgkmcnt(5)
	v_mfma_f32_32x32x16_bf16 v[16:31], v[208:211], v[152:155], v[16:31]
	ds_read_b128 v[208:211], v182 offset:0
	v_add_f32_e32 v190, v190, v179
	v_add_f32_e32 v191, v191, v180
	v_add_f32_e32 v190, v190, v232
	v_add_f32_e32 v191, v191, v233
	s_waitcnt lgkmcnt(5)
	v_mfma_f32_32x32x16_bf16 v[0:15], v[212:215], v[152:155], v[0:15]
	ds_read_b128 v[212:215], v182 offset:4096
	v_add_f32_e32 v190, v190, v234
	v_add_f32_e32 v191, v191, v235
	v_cvt_pk_bf16_f32 v148, v171, v173
	v_cvt_pk_bf16_f32 v149, v179, v180
	s_waitcnt lgkmcnt(5)
	v_mfma_f32_32x32x16_bf16 v[48:63], v[216:219], v[156:159], v[48:63]
	ds_read_b128 v[216:219], v183 offset:0
	v_cvt_pk_bf16_f32 v150, v232, v233
	v_cvt_pk_bf16_f32 v151, v234, v235
	v_exp_f32_e32 v171, v112
	v_exp_f32_e32 v173, v113
	s_waitcnt lgkmcnt(5)
	v_mfma_f32_32x32x16_bf16 v[32:47], v[220:223], v[156:159], v[32:47]
	ds_read_b128 v[220:223], v183 offset:4096
	v_exp_f32_e32 v179, v114
	v_exp_f32_e32 v180, v115
	v_exp_f32_e32 v232, v116
	v_exp_f32_e32 v233, v117
	s_waitcnt lgkmcnt(5)
	v_mfma_f32_32x32x16_bf16 v[16:31], v[224:227], v[156:159], v[16:31]
	ds_read_b128 v[224:227], v184 offset:0
	v_exp_f32_e32 v234, v118
	v_exp_f32_e32 v235, v119
	v_add_f32_e32 v190, v190, v171
	v_add_f32_e32 v191, v191, v173
	s_waitcnt lgkmcnt(5)
	v_mfma_f32_32x32x16_bf16 v[0:15], v[228:231], v[156:159], v[0:15]
	ds_read_b128 v[228:231], v184 offset:4096
	v_add_f32_e32 v190, v190, v179
	v_add_f32_e32 v191, v191, v180
	v_add_f32_e32 v190, v190, v232
	v_add_f32_e32 v191, v191, v233
	s_waitcnt lgkmcnt(5)
	v_mfma_f32_32x32x16_bf16 v[64:79], v[208:211], v[128:131], 0
	ds_read_b128 v[208:211], v185 offset:0
	v_add_f32_e32 v190, v190, v234
	v_add_f32_e32 v191, v191, v235
	v_cvt_pk_bf16_f32 v152, v171, v173
	v_cvt_pk_bf16_f32 v153, v179, v180
	s_waitcnt lgkmcnt(5)
	v_mfma_f32_32x32x16_bf16 v[80:95], v[212:215], v[128:131], 0
	ds_read_b128 v[212:215], v185 offset:4096
	v_cvt_pk_bf16_f32 v154, v232, v233
	v_cvt_pk_bf16_f32 v155, v234, v235
	v_exp_f32_e32 v171, v120
	v_exp_f32_e32 v173, v121
	s_waitcnt lgkmcnt(5)
	v_mfma_f32_32x32x16_bf16 v[64:79], v[216:219], v[132:135], v[64:79]
	ds_read_b128 v[216:219], v187 offset:49152
	v_exp_f32_e32 v179, v122
	v_exp_f32_e32 v180, v123
	v_exp_f32_e32 v232, v124
	v_exp_f32_e32 v233, v125
	s_waitcnt lgkmcnt(5)
	v_mfma_f32_32x32x16_bf16 v[80:95], v[220:223], v[132:135], v[80:95]
	ds_read_b128 v[220:223], v187 offset:53248
	v_exp_f32_e32 v234, v126
	v_exp_f32_e32 v235, v127
	v_add_f32_e32 v190, v190, v171
	s_waitcnt lgkmcnt(5)
	v_mfma_f32_32x32x16_bf16 v[64:79], v[224:227], v[136:139], v[64:79]
	ds_read_b128 v[224:227], v187 offset:57344
	v_add_f32_e32 v191, v191, v173
	v_add_f32_e32 v190, v190, v179
	v_add_f32_e32 v191, v191, v180
	s_waitcnt lgkmcnt(5)
	v_mfma_f32_32x32x16_bf16 v[80:95], v[228:231], v[136:139], v[80:95]
	ds_read_b128 v[228:231], v187 offset:61440
	v_add_f32_e32 v190, v190, v232
	v_add_f32_e32 v191, v191, v233
	v_add_f32_e32 v190, v190, v234
	s_waitcnt lgkmcnt(5)
	v_mfma_f32_32x32x16_bf16 v[64:79], v[208:211], v[140:143], v[64:79]
	ds_read_b128 v[208:211], v188 offset:49152
	v_add_f32_e32 v191, v191, v235
	v_cvt_pk_bf16_f32 v156, v171, v173
	v_cvt_pk_bf16_f32 v157, v179, v180
	s_waitcnt lgkmcnt(5)
	v_mfma_f32_32x32x16_bf16 v[80:95], v[212:215], v[140:143], v[80:95]
	ds_read_b128 v[212:215], v188 offset:53248
	v_cvt_pk_bf16_f32 v158, v232, v233
	v_cvt_pk_bf16_f32 v159, v234, v235
	v_add_f32_e32 v190, v190, v191
	v_cmp_ngt_f32_e32 vcc, 0x71800000, v190
	s_nop 4
	s_cbranch_vccnz .Lattn_redo_L2
	v_add_f32_e32 v167, v167, v190
	s_waitcnt vmcnt(4)
	s_barrier
	s_waitcnt lgkmcnt(5)
	v_mfma_f32_32x32x16_bf16 v[48:63], v[216:219], v[144:147], v[48:63]
	ds_read_b128 v[216:219], v188 offset:57344
	s_add_i32 s2, s42, 6
	s_and_b32 s2, s2, 31
	s_mul_i32 s2, s2, 0x44000
	s_add_i32 m0, s5, 49152
	s_add_u32 s40, s26, s2
	s_addc_u32 s41, s27, 0
	global_load_lds_dwordx4 v170, s[40:41]
	s_add_i32 m0, s5, 57344
	s_waitcnt lgkmcnt(5)
	v_mfma_f32_32x32x16_bf16 v[32:47], v[220:223], v[144:147], v[32:47]
	ds_read_b128 v[220:223], v188 offset:61440
	s_add_u32 s40, s40, 0x80
	s_addc_u32 s41, s41, 0
	global_load_lds_dwordx4 v170, s[40:41]
	s_add_i32 s2, s42, 5
	s_and_b32 s2, s2, 31
	s_lshl_b32 s2, s2, 7
	s_add_i32 m0, s5, 98304
	s_add_u32 s44, s10, s2
	s_waitcnt lgkmcnt(5)
	v_mfma_f32_32x32x16_bf16 v[16:31], v[224:227], v[144:147], v[16:31]
	ds_read_b128 v[224:227], v186 offset:49152
	s_addc_u32 s45, s11, 0
	global_load_lds_dwordx4 v172, s[44:45]
	s_add_i32 m0, s5, 106496
	s_add_u32 s44, s44, 0x204000
	s_addc_u32 s45, s45, 0
	global_load_lds_dwordx4 v172, s[44:45]
	s_waitcnt lgkmcnt(5)
	v_mfma_f32_32x32x16_bf16 v[0:15], v[228:231], v[144:147], v[0:15]
	ds_read_b128 v[228:231], v186 offset:53248
	v_exp_f32_e32 v171, v64
	v_exp_f32_e32 v173, v65
	v_exp_f32_e32 v179, v66
	v_exp_f32_e32 v180, v67
	s_waitcnt lgkmcnt(5)
	v_mfma_f32_32x32x16_bf16 v[48:63], v[208:211], v[148:151], v[48:63]
	ds_read_b128 v[208:211], v186 offset:57344
	v_exp_f32_e32 v232, v68
	v_exp_f32_e32 v233, v69
	v_exp_f32_e32 v234, v70
	v_exp_f32_e32 v235, v71
	s_waitcnt lgkmcnt(5)
	v_mfma_f32_32x32x16_bf16 v[32:47], v[212:215], v[148:151], v[32:47]
	ds_read_b128 v[212:215], v186 offset:61440
	v_add_f32_e32 v190, v171, v173
	v_add_f32_e32 v191, v179, v180
	v_add_f32_e32 v190, v190, v232
	v_add_f32_e32 v191, v191, v233
	s_waitcnt lgkmcnt(5)
	v_mfma_f32_32x32x16_bf16 v[16:31], v[216:219], v[148:151], v[16:31]
	ds_read_b128 v[216:219], v189 offset:49152
	v_add_f32_e32 v190, v190, v234
	v_add_f32_e32 v191, v191, v235
	v_cvt_pk_bf16_f32 v144, v171, v173
	v_cvt_pk_bf16_f32 v145, v179, v180
	s_waitcnt lgkmcnt(5)
	v_mfma_f32_32x32x16_bf16 v[0:15], v[220:223], v[148:151], v[0:15]
	ds_read_b128 v[220:223], v189 offset:53248
	v_cvt_pk_bf16_f32 v146, v232, v233
	v_cvt_pk_bf16_f32 v147, v234, v235
	v_exp_f32_e32 v171, v72
	v_exp_f32_e32 v173, v73
	s_waitcnt lgkmcnt(5)
	v_mfma_f32_32x32x16_bf16 v[48:63], v[224:227], v[152:155], v[48:63]
	ds_read_b128 v[224:227], v189 offset:57344
	v_exp_f32_e32 v179, v74
	v_exp_f32_e32 v180, v75
	v_exp_f32_e32 v232, v76
	v_exp_f32_e32 v233, v77
	s_waitcnt lgkmcnt(5)
	v_mfma_f32_32x32x16_bf16 v[32:47], v[228:231], v[152:155], v[32:47]
	ds_read_b128 v[228:231], v189 offset:61440
	v_exp_f32_e32 v234, v78
	v_exp_f32_e32 v235, v79
	v_add_f32_e32 v190, v190, v171
	v_add_f32_e32 v191, v191, v173
	s_waitcnt lgkmcnt(5)
	v_mfma_f32_32x32x16_bf16 v[16:31], v[208:211], v[152:155], v[16:31]
	ds_read_b128 v[208:211], v182 offset:16384
	v_add_f32_e32 v190, v190, v179
	v_add_f32_e32 v191, v191, v180
	v_add_f32_e32 v190, v190, v232
	v_add_f32_e32 v191, v191, v233
	s_waitcnt lgkmcnt(5)
	v_mfma_f32_32x32x16_bf16 v[0:15], v[212:215], v[152:155], v[0:15]
	ds_read_b128 v[212:215], v182 offset:20480
	v_add_f32_e32 v190, v190, v234
	v_add_f32_e32 v191, v191, v235
	v_cvt_pk_bf16_f32 v148, v171, v173
	v_cvt_pk_bf16_f32 v149, v179, v180
	s_waitcnt lgkmcnt(5)
	v_mfma_f32_32x32x16_bf16 v[48:63], v[216:219], v[156:159], v[48:63]
	ds_read_b128 v[216:219], v183 offset:16384
	v_cvt_pk_bf16_f32 v150, v232, v233
	v_cvt_pk_bf16_f32 v151, v234, v235
	v_exp_f32_e32 v171, v80
	v_exp_f32_e32 v173, v81
	s_waitcnt lgkmcnt(5)
	v_mfma_f32_32x32x16_bf16 v[32:47], v[220:223], v[156:159], v[32:47]
	ds_read_b128 v[220:223], v183 offset:20480
	v_exp_f32_e32 v179, v82
	v_exp_f32_e32 v180, v83
	v_exp_f32_e32 v232, v84
	v_exp_f32_e32 v233, v85
	s_waitcnt lgkmcnt(5)
	v_mfma_f32_32x32x16_bf16 v[16:31], v[224:227], v[156:159], v[16:31]
	ds_read_b128 v[224:227], v184 offset:16384
	v_exp_f32_e32 v234, v86
	v_exp_f32_e32 v235, v87
	v_add_f32_e32 v190, v190, v171
	v_add_f32_e32 v191, v191, v173
	s_waitcnt lgkmcnt(5)
	v_mfma_f32_32x32x16_bf16 v[0:15], v[228:231], v[156:159], v[0:15]
	ds_read_b128 v[228:231], v184 offset:20480
	v_add_f32_e32 v190, v190, v179
	v_add_f32_e32 v191, v191, v180
	v_add_f32_e32 v190, v190, v232
	v_add_f32_e32 v191, v191, v233
	s_waitcnt lgkmcnt(5)
	v_mfma_f32_32x32x16_bf16 v[96:111], v[208:211], v[128:131], 0
	ds_read_b128 v[208:211], v185 offset:16384
	v_add_f32_e32 v190, v190, v234
	v_add_f32_e32 v191, v191, v235
	v_cvt_pk_bf16_f32 v152, v171, v173
	v_cvt_pk_bf16_f32 v153, v179, v180
	s_waitcnt lgkmcnt(5)
	v_mfma_f32_32x32x16_bf16 v[112:127], v[212:215], v[128:131], 0
	ds_read_b128 v[212:215], v185 offset:20480
	v_cvt_pk_bf16_f32 v154, v232, v233
	v_cvt_pk_bf16_f32 v155, v234, v235
	v_exp_f32_e32 v171, v88
	v_exp_f32_e32 v173, v89
	s_waitcnt lgkmcnt(5)
	v_mfma_f32_32x32x16_bf16 v[96:111], v[216:219], v[132:135], v[96:111]
	ds_read_b128 v[216:219], v187 offset:0
	v_exp_f32_e32 v179, v90
	v_exp_f32_e32 v180, v91
	v_exp_f32_e32 v232, v92
	v_exp_f32_e32 v233, v93
	s_waitcnt lgkmcnt(5)
	v_mfma_f32_32x32x16_bf16 v[112:127], v[220:223], v[132:135], v[112:127]
	ds_read_b128 v[220:223], v187 offset:4096
	v_exp_f32_e32 v234, v94
	v_exp_f32_e32 v235, v95
	v_add_f32_e32 v190, v190, v171
	s_waitcnt lgkmcnt(5)
	v_mfma_f32_32x32x16_bf16 v[96:111], v[224:227], v[136:139], v[96:111]
	ds_read_b128 v[224:227], v187 offset:8192
	v_add_f32_e32 v191, v191, v173
	v_add_f32_e32 v190, v190, v179
	v_add_f32_e32 v191, v191, v180
	s_waitcnt lgkmcnt(5)
	v_mfma_f32_32x32x16_bf16 v[112:127], v[228:231], v[136:139], v[112:127]
	ds_read_b128 v[228:231], v187 offset:12288
	v_add_f32_e32 v190, v190, v232
	v_add_f32_e32 v191, v191, v233
	v_add_f32_e32 v190, v190, v234
	s_waitcnt lgkmcnt(5)
	v_mfma_f32_32x32x16_bf16 v[96:111], v[208:211], v[140:143], v[96:111]
	ds_read_b128 v[208:211], v188 offset:0
	v_add_f32_e32 v191, v191, v235
	v_cvt_pk_bf16_f32 v156, v171, v173
	v_cvt_pk_bf16_f32 v157, v179, v180
	s_waitcnt lgkmcnt(5)
	v_mfma_f32_32x32x16_bf16 v[112:127], v[212:215], v[140:143], v[112:127]
	ds_read_b128 v[212:215], v188 offset:4096
	v_cvt_pk_bf16_f32 v158, v232, v233
	v_cvt_pk_bf16_f32 v159, v234, v235
	v_add_f32_e32 v190, v190, v191
	v_cmp_ngt_f32_e32 vcc, 0x71800000, v190
	s_nop 4
	s_cbranch_vccnz .Lattn_redo_L3
	v_add_f32_e32 v167, v167, v190
	s_add_i32 s42, s42, 4
	s_add_i32 s47, s47, -1
	s_cmp_lg_u32 s47, 0
	s_cbranch_scc1 .Lattn_loop_f
	s_waitcnt vmcnt(4)
	s_barrier
	s_waitcnt lgkmcnt(5)
	v_mfma_f32_32x32x16_bf16 v[48:63], v[216:219], v[144:147], v[48:63]
	ds_read_b128 v[216:219], v188 offset:8192
	s_add_i32 s2, s42, 2
	s_and_b32 s2, s2, 31
	s_lshl_b32 s2, s2, 7
	s_add_i32 m0, s5, 114688
	s_add_u32 s44, s10, s2
	s_addc_u32 s45, s11, 0
	global_load_lds_dwordx4 v172, s[44:45]
	s_add_i32 m0, s5, 122880
	s_waitcnt lgkmcnt(5)
	v_mfma_f32_32x32x16_bf16 v[32:47], v[220:223], v[144:147], v[32:47]
	ds_read_b128 v[220:223], v188 offset:12288
	s_add_u32 s44, s44, 0x204000
	s_addc_u32 s45, s45, 0
	global_load_lds_dwordx4 v172, s[44:45]
	s_waitcnt lgkmcnt(5)
	v_mfma_f32_32x32x16_bf16 v[16:31], v[224:227], v[144:147], v[16:31]
	ds_read_b128 v[224:227], v186 offset:0
	s_waitcnt lgkmcnt(5)
	v_mfma_f32_32x32x16_bf16 v[0:15], v[228:231], v[144:147], v[0:15]
	ds_read_b128 v[228:231], v186 offset:4096
	v_exp_f32_e32 v171, v96
	v_exp_f32_e32 v173, v97
	v_exp_f32_e32 v179, v98
	v_exp_f32_e32 v180, v99
	s_waitcnt lgkmcnt(5)
	v_mfma_f32_32x32x16_bf16 v[48:63], v[208:211], v[148:151], v[48:63]
	ds_read_b128 v[208:211], v186 offset:8192
	v_exp_f32_e32 v232, v100
	v_exp_f32_e32 v233, v101
	v_exp_f32_e32 v234, v102
	v_exp_f32_e32 v235, v103
	s_waitcnt lgkmcnt(5)
	v_mfma_f32_32x32x16_bf16 v[32:47], v[212:215], v[148:151], v[32:47]
	ds_read_b128 v[212:215], v186 offset:12288
	v_add_f32_e32 v190, v171, v173
	v_add_f32_e32 v191, v179, v180
	v_add_f32_e32 v190, v190, v232
	v_add_f32_e32 v191, v191, v233
	s_waitcnt lgkmcnt(5)
	v_mfma_f32_32x32x16_bf16 v[16:31], v[216:219], v[148:151], v[16:31]
	ds_read_b128 v[216:219], v189 offset:0
	v_add_f32_e32 v190, v190, v234
	v_add_f32_e32 v191, v191, v235
	v_cvt_pk_bf16_f32 v144, v171, v173
	v_cvt_pk_bf16_f32 v145, v179, v180
	s_waitcnt lgkmcnt(5)
	v_mfma_f32_32x32x16_bf16 v[0:15], v[220:223], v[148:151], v[0:15]
	ds_read_b128 v[220:223], v189 offset:4096
	v_cvt_pk_bf16_f32 v146, v232, v233
	v_cvt_pk_bf16_f32 v147, v234, v235
	v_exp_f32_e32 v171, v104
	v_exp_f32_e32 v173, v105
	s_waitcnt lgkmcnt(5)
	v_mfma_f32_32x32x16_bf16 v[48:63], v[224:227], v[152:155], v[48:63]
	ds_read_b128 v[224:227], v189 offset:8192
	v_exp_f32_e32 v179, v106
	v_exp_f32_e32 v180, v107
	v_exp_f32_e32 v232, v108
	v_exp_f32_e32 v233, v109
	s_waitcnt lgkmcnt(5)
	v_mfma_f32_32x32x16_bf16 v[32:47], v[228:231], v[152:155], v[32:47]
	ds_read_b128 v[228:231], v189 offset:12288
	v_exp_f32_e32 v234, v110
	v_exp_f32_e32 v235, v111
	v_add_f32_e32 v190, v190, v171
	v_add_f32_e32 v191, v191, v173
	s_waitcnt lgkmcnt(5)
	v_mfma_f32_32x32x16_bf16 v[16:31], v[208:211], v[152:155], v[16:31]
	ds_read_b128 v[208:211], v182 offset:32768
	v_add_f32_e32 v190, v190, v179
	v_add_f32_e32 v191, v191, v180
	v_add_f32_e32 v190, v190, v232
	v_add_f32_e32 v191, v191, v233
	s_waitcnt lgkmcnt(5)
	v_mfma_f32_32x32x16_bf16 v[0:15], v[212:215], v[152:155], v[0:15]
	ds_read_b128 v[212:215], v182 offset:36864
	v_add_f32_e32 v190, v190, v234
	v_add_f32_e32 v191, v191, v235
	v_cvt_pk_bf16_f32 v148, v171, v173
	v_cvt_pk_bf16_f32 v149, v179, v180
	s_waitcnt lgkmcnt(5)
	v_mfma_f32_32x32x16_bf16 v[48:63], v[216:219], v[156:159], v[48:63]
	ds_read_b128 v[216:219], v183 offset:32768
	v_cvt_pk_bf16_f32 v150, v232, v233
	v_cvt_pk_bf16_f32 v151, v234, v235
	v_exp_f32_e32 v171, v112
	v_exp_f32_e32 v173, v113
	s_waitcnt lgkmcnt(5)
	v_mfma_f32_32x32x16_bf16 v[32:47], v[220:223], v[156:159], v[32:47]
	ds_read_b128 v[220:223], v183 offset:36864
	v_exp_f32_e32 v179, v114
	v_exp_f32_e32 v180, v115
	v_exp_f32_e32 v232, v116
	v_exp_f32_e32 v233, v117
	s_waitcnt lgkmcnt(5)
	v_mfma_f32_32x32x16_bf16 v[16:31], v[224:227], v[156:159], v[16:31]
	ds_read_b128 v[224:227], v184 offset:32768
	v_exp_f32_e32 v234, v118
	v_exp_f32_e32 v235, v119
	v_add_f32_e32 v190, v190, v171
	v_add_f32_e32 v191, v191, v173
	s_waitcnt lgkmcnt(5)
	v_mfma_f32_32x32x16_bf16 v[0:15], v[228:231], v[156:159], v[0:15]
	ds_read_b128 v[228:231], v184 offset:36864
	v_add_f32_e32 v190, v190, v179
	v_add_f32_e32 v191, v191, v180
	v_add_f32_e32 v190, v190, v232
	v_add_f32_e32 v191, v191, v233
	s_waitcnt lgkmcnt(5)
	v_mfma_f32_32x32x16_bf16 v[64:79], v[208:211], v[128:131], 0
	ds_read_b128 v[208:211], v185 offset:32768
	v_add_f32_e32 v190, v190, v234
	v_add_f32_e32 v191, v191, v235
	v_cvt_pk_bf16_f32 v152, v171, v173
	v_cvt_pk_bf16_f32 v153, v179, v180
	s_waitcnt lgkmcnt(5)
	v_mfma_f32_32x32x16_bf16 v[80:95], v[212:215], v[128:131], 0
	ds_read_b128 v[212:215], v185 offset:36864
	v_cvt_pk_bf16_f32 v154, v232, v233
	v_cvt_pk_bf16_f32 v155, v234, v235
	v_exp_f32_e32 v171, v120
	v_exp_f32_e32 v173, v121
	s_waitcnt lgkmcnt(5)
	v_mfma_f32_32x32x16_bf16 v[64:79], v[216:219], v[132:135], v[64:79]
	ds_read_b128 v[216:219], v187 offset:16384
	v_exp_f32_e32 v179, v122
	v_exp_f32_e32 v180, v123
	v_exp_f32_e32 v232, v124
	v_exp_f32_e32 v233, v125
	s_waitcnt lgkmcnt(5)
	v_mfma_f32_32x32x16_bf16 v[80:95], v[220:223], v[132:135], v[80:95]
	ds_read_b128 v[220:223], v187 offset:20480
	v_exp_f32_e32 v234, v126
	v_exp_f32_e32 v235, v127
	v_add_f32_e32 v190, v190, v171
	s_waitcnt lgkmcnt(5)
	v_mfma_f32_32x32x16_bf16 v[64:79], v[224:227], v[136:139], v[64:79]
	ds_read_b128 v[224:227], v187 offset:24576
	v_add_f32_e32 v191, v191, v173
	v_add_f32_e32 v190, v190, v179
	v_add_f32_e32 v191, v191, v180
	s_waitcnt lgkmcnt(5)
	v_mfma_f32_32x32x16_bf16 v[80:95], v[228:231], v[136:139], v[80:95]
	ds_read_b128 v[228:231], v187 offset:28672
	v_add_f32_e32 v190, v190, v232
	v_add_f32_e32 v191, v191, v233
	v_add_f32_e32 v190, v190, v234
	s_waitcnt lgkmcnt(5)
	v_mfma_f32_32x32x16_bf16 v[64:79], v[208:211], v[140:143], v[64:79]
	ds_read_b128 v[208:211], v188 offset:16384
	v_add_f32_e32 v191, v191, v235
	v_cvt_pk_bf16_f32 v156, v171, v173
	v_cvt_pk_bf16_f32 v157, v179, v180
	s_waitcnt lgkmcnt(5)
	v_mfma_f32_32x32x16_bf16 v[80:95], v[212:215], v[140:143], v[80:95]
	ds_read_b128 v[212:215], v188 offset:20480
	v_cvt_pk_bf16_f32 v158, v232, v233
	v_cvt_pk_bf16_f32 v159, v234, v235
	v_add_f32_e32 v190, v190, v191
	v_cmp_ngt_f32_e32 vcc, 0x71800000, v190
	s_nop 4
	s_cbranch_vccnz .Lattn_redo_T29
	v_add_f32_e32 v167, v167, v190
	s_waitcnt vmcnt(2)
	s_barrier
	s_waitcnt lgkmcnt(5)
	v_mfma_f32_32x32x16_bf16 v[48:63], v[216:219], v[144:147], v[48:63]
	ds_read_b128 v[216:219], v188 offset:24576
	s_waitcnt lgkmcnt(5)
	v_mfma_f32_32x32x16_bf16 v[32:47], v[220:223], v[144:147], v[32:47]
	ds_read_b128 v[220:223], v188 offset:28672
	s_waitcnt lgkmcnt(5)
	v_mfma_f32_32x32x16_bf16 v[16:31], v[224:227], v[144:147], v[16:31]
	ds_read_b128 v[224:227], v186 offset:16384
	s_waitcnt lgkmcnt(5)
	v_mfma_f32_32x32x16_bf16 v[0:15], v[228:231], v[144:147], v[0:15]
	ds_read_b128 v[228:231], v186 offset:20480
	v_exp_f32_e32 v171, v64
	v_exp_f32_e32 v173, v65
	v_exp_f32_e32 v179, v66
	v_exp_f32_e32 v180, v67
	s_waitcnt lgkmcnt(5)
	v_mfma_f32_32x32x16_bf16 v[48:63], v[208:211], v[148:151], v[48:63]
	ds_read_b128 v[208:211], v186 offset:24576
	v_exp_f32_e32 v232, v68
	v_exp_f32_e32 v233, v69
	v_exp_f32_e32 v234, v70
	v_exp_f32_e32 v235, v71
	s_waitcnt lgkmcnt(5)
	v_mfma_f32_32x32x16_bf16 v[32:47], v[212:215], v[148:151], v[32:47]
	ds_read_b128 v[212:215], v186 offset:28672
	v_add_f32_e32 v190, v171, v173
	v_add_f32_e32 v191, v179, v180
	v_add_f32_e32 v190, v190, v232
	v_add_f32_e32 v191, v191, v233
	s_waitcnt lgkmcnt(5)
	v_mfma_f32_32x32x16_bf16 v[16:31], v[216:219], v[148:151], v[16:31]
	ds_read_b128 v[216:219], v189 offset:16384
	v_add_f32_e32 v190, v190, v234
	v_add_f32_e32 v191, v191, v235
	v_cvt_pk_bf16_f32 v144, v171, v173
	v_cvt_pk_bf16_f32 v145, v179, v180
	s_waitcnt lgkmcnt(5)
	v_mfma_f32_32x32x16_bf16 v[0:15], v[220:223], v[148:151], v[0:15]
	ds_read_b128 v[220:223], v189 offset:20480
	v_cvt_pk_bf16_f32 v146, v232, v233
	v_cvt_pk_bf16_f32 v147, v234, v235
	v_exp_f32_e32 v171, v72
	v_exp_f32_e32 v173, v73
	s_waitcnt lgkmcnt(5)
	v_mfma_f32_32x32x16_bf16 v[48:63], v[224:227], v[152:155], v[48:63]
	ds_read_b128 v[224:227], v189 offset:24576
	v_exp_f32_e32 v179, v74
	v_exp_f32_e32 v180, v75
	v_exp_f32_e32 v232, v76
	v_exp_f32_e32 v233, v77
	s_waitcnt lgkmcnt(5)
	v_mfma_f32_32x32x16_bf16 v[32:47], v[228:231], v[152:155], v[32:47]
	ds_read_b128 v[228:231], v189 offset:28672
	v_exp_f32_e32 v234, v78
	v_exp_f32_e32 v235, v79
	v_add_f32_e32 v190, v190, v171
	v_add_f32_e32 v191, v191, v173
	s_waitcnt lgkmcnt(5)
	v_mfma_f32_32x32x16_bf16 v[16:31], v[208:211], v[152:155], v[16:31]
	ds_read_b128 v[208:211], v182 offset:49152
	v_add_f32_e32 v190, v190, v179
	v_add_f32_e32 v191, v191, v180
	v_add_f32_e32 v190, v190, v232
	v_add_f32_e32 v191, v191, v233
	s_waitcnt lgkmcnt(5)
	v_mfma_f32_32x32x16_bf16 v[0:15], v[212:215], v[152:155], v[0:15]
	ds_read_b128 v[212:215], v182 offset:53248
	v_add_f32_e32 v190, v190, v234
	v_add_f32_e32 v191, v191, v235
	v_cvt_pk_bf16_f32 v148, v171, v173
	v_cvt_pk_bf16_f32 v149, v179, v180
	s_waitcnt lgkmcnt(5)
	v_mfma_f32_32x32x16_bf16 v[48:63], v[216:219], v[156:159], v[48:63]
	ds_read_b128 v[216:219], v183 offset:49152
	v_cvt_pk_bf16_f32 v150, v232, v233
	v_cvt_pk_bf16_f32 v151, v234, v235
	v_exp_f32_e32 v171, v80
	v_exp_f32_e32 v173, v81
	s_waitcnt lgkmcnt(5)
	v_mfma_f32_32x32x16_bf16 v[32:47], v[220:223], v[156:159], v[32:47]
	ds_read_b128 v[220:223], v183 offset:53248
	v_exp_f32_e32 v179, v82
	v_exp_f32_e32 v180, v83
	v_exp_f32_e32 v232, v84
	v_exp_f32_e32 v233, v85
	s_waitcnt lgkmcnt(5)
	v_mfma_f32_32x32x16_bf16 v[16:31], v[224:227], v[156:159], v[16:31]
	ds_read_b128 v[224:227], v184 offset:49152
	v_exp_f32_e32 v234, v86
	v_exp_f32_e32 v235, v87
	v_add_f32_e32 v190, v190, v171
	v_add_f32_e32 v191, v191, v173
	s_waitcnt lgkmcnt(5)
	v_mfma_f32_32x32x16_bf16 v[0:15], v[228:231], v[156:159], v[0:15]
	ds_read_b128 v[228:231], v184 offset:53248
	v_add_f32_e32 v190, v190, v179
	v_add_f32_e32 v191, v191, v180
	v_add_f32_e32 v190, v190, v232
	v_add_f32_e32 v191, v191, v233
	s_waitcnt lgkmcnt(5)
	v_mfma_f32_32x32x16_bf16 v[96:111], v[208:211], v[128:131], 0
	ds_read_b128 v[208:211], v185 offset:49152
	v_add_f32_e32 v190, v190, v234
	v_add_f32_e32 v191, v191, v235
	v_cvt_pk_bf16_f32 v152, v171, v173
	v_cvt_pk_bf16_f32 v153, v179, v180
	s_waitcnt lgkmcnt(5)
	v_mfma_f32_32x32x16_bf16 v[112:127], v[212:215], v[128:131], 0
	ds_read_b128 v[212:215], v185 offset:53248
	v_cvt_pk_bf16_f32 v154, v232, v233
	v_cvt_pk_bf16_f32 v155, v234, v235
	v_exp_f32_e32 v171, v88
	v_exp_f32_e32 v173, v89
	s_waitcnt lgkmcnt(5)
	v_mfma_f32_32x32x16_bf16 v[96:111], v[216:219], v[132:135], v[96:111]
	ds_read_b128 v[216:219], v187 offset:32768
	v_exp_f32_e32 v179, v90
	v_exp_f32_e32 v180, v91
	v_exp_f32_e32 v232, v92
	v_exp_f32_e32 v233, v93
	s_waitcnt lgkmcnt(5)
	v_mfma_f32_32x32x16_bf16 v[112:127], v[220:223], v[132:135], v[112:127]
	ds_read_b128 v[220:223], v187 offset:36864
	v_exp_f32_e32 v234, v94
	v_exp_f32_e32 v235, v95
	v_add_f32_e32 v190, v190, v171
	s_waitcnt lgkmcnt(5)
	v_mfma_f32_32x32x16_bf16 v[96:111], v[224:227], v[136:139], v[96:111]
	ds_read_b128 v[224:227], v187 offset:40960
	v_add_f32_e32 v191, v191, v173
	v_add_f32_e32 v190, v190, v179
	v_add_f32_e32 v191, v191, v180
	s_waitcnt lgkmcnt(5)
	v_mfma_f32_32x32x16_bf16 v[112:127], v[228:231], v[136:139], v[112:127]
	ds_read_b128 v[228:231], v187 offset:45056
	v_add_f32_e32 v190, v190, v232
	v_add_f32_e32 v191, v191, v233
	v_add_f32_e32 v190, v190, v234
	s_waitcnt lgkmcnt(5)
	v_mfma_f32_32x32x16_bf16 v[96:111], v[208:211], v[140:143], v[96:111]
	ds_read_b128 v[208:211], v188 offset:32768
	v_add_f32_e32 v191, v191, v235
	v_cvt_pk_bf16_f32 v156, v171, v173
	v_cvt_pk_bf16_f32 v157, v179, v180
	s_waitcnt lgkmcnt(5)
	v_mfma_f32_32x32x16_bf16 v[112:127], v[212:215], v[140:143], v[112:127]
	ds_read_b128 v[212:215], v188 offset:36864
	v_cvt_pk_bf16_f32 v158, v232, v233
	v_cvt_pk_bf16_f32 v159, v234, v235
	v_add_f32_e32 v190, v190, v191
	v_cmp_ngt_f32_e32 vcc, 0x71800000, v190
	s_nop 4
	s_cbranch_vccnz .Lattn_redo_T30
	v_add_f32_e32 v167, v167, v190
	s_waitcnt vmcnt(0)
	s_barrier
	s_waitcnt lgkmcnt(5)
	v_mfma_f32_32x32x16_bf16 v[48:63], v[216:219], v[144:147], v[48:63]
	ds_read_b128 v[216:219], v188 offset:40960
	s_waitcnt lgkmcnt(5)
	v_mfma_f32_32x32x16_bf16 v[32:47], v[220:223], v[144:147], v[32:47]
	ds_read_b128 v[220:223], v188 offset:45056
	s_waitcnt lgkmcnt(5)
	v_mfma_f32_32x32x16_bf16 v[16:31], v[224:227], v[144:147], v[16:31]
	ds_read_b128 v[224:227], v186 offset:32768
	s_waitcnt lgkmcnt(5)
	v_mfma_f32_32x32x16_bf16 v[0:15], v[228:231], v[144:147], v[0:15]
	ds_read_b128 v[228:231], v186 offset:36864
	v_exp_f32_e32 v171, v96
	v_exp_f32_e32 v173, v97
	v_exp_f32_e32 v179, v98
	v_exp_f32_e32 v180, v99
	v_exp_f32_e32 v232, v100
	v_exp_f32_e32 v233, v101
	v_exp_f32_e32 v234, v102
	s_waitcnt lgkmcnt(5)
	v_mfma_f32_32x32x16_bf16 v[48:63], v[208:211], v[148:151], v[48:63]
	ds_read_b128 v[208:211], v186 offset:40960
	v_exp_f32_e32 v235, v103
	v_add_f32_e32 v190, v171, v173
	v_add_f32_e32 v191, v179, v180
	v_add_f32_e32 v190, v190, v232
	v_add_f32_e32 v191, v191, v233
	v_add_f32_e32 v190, v190, v234
	s_waitcnt lgkmcnt(5)
	v_mfma_f32_32x32x16_bf16 v[32:47], v[212:215], v[148:151], v[32:47]
	ds_read_b128 v[212:215], v186 offset:45056
	v_add_f32_e32 v191, v191, v235
	v_cvt_pk_bf16_f32 v144, v171, v173
	v_cvt_pk_bf16_f32 v145, v179, v180
	v_cvt_pk_bf16_f32 v146, v232, v233
	v_cvt_pk_bf16_f32 v147, v234, v235
	s_waitcnt lgkmcnt(5)
	v_mfma_f32_32x32x16_bf16 v[16:31], v[216:219], v[148:151], v[16:31]
	ds_read_b128 v[216:219], v189 offset:32768
	s_waitcnt lgkmcnt(5)
	v_mfma_f32_32x32x16_bf16 v[0:15], v[220:223], v[148:151], v[0:15]
	ds_read_b128 v[220:223], v189 offset:36864
	v_exp_f32_e32 v171, v104
	v_exp_f32_e32 v173, v105
	v_exp_f32_e32 v179, v106
	v_exp_f32_e32 v180, v107
	v_exp_f32_e32 v232, v108
	v_exp_f32_e32 v233, v109
	v_exp_f32_e32 v234, v110
	s_waitcnt lgkmcnt(5)
	v_mfma_f32_32x32x16_bf16 v[48:63], v[224:227], v[152:155], v[48:63]
	ds_read_b128 v[224:227], v189 offset:40960
	v_exp_f32_e32 v235, v111
	v_add_f32_e32 v190, v190, v171
	v_add_f32_e32 v191, v191, v173
	v_add_f32_e32 v190, v190, v179
	v_add_f32_e32 v191, v191, v180
	v_add_f32_e32 v190, v190, v232
	v_add_f32_e32 v191, v191, v233
	s_waitcnt lgkmcnt(5)
	v_mfma_f32_32x32x16_bf16 v[32:47], v[228:231], v[152:155], v[32:47]
	ds_read_b128 v[228:231], v189 offset:45056
	v_add_f32_e32 v190, v190, v234
	v_add_f32_e32 v191, v191, v235
	v_cvt_pk_bf16_f32 v148, v171, v173
	v_cvt_pk_bf16_f32 v149, v179, v180
	v_cvt_pk_bf16_f32 v150, v232, v233
	v_cvt_pk_bf16_f32 v151, v234, v235
	s_waitcnt lgkmcnt(5)
	v_mfma_f32_32x32x16_bf16 v[16:31], v[208:211], v[152:155], v[16:31]
	ds_read_b128 v[208:211], v187 offset:49152
	s_waitcnt lgkmcnt(5)
	v_mfma_f32_32x32x16_bf16 v[0:15], v[212:215], v[152:155], v[0:15]
	ds_read_b128 v[212:215], v187 offset:53248
	v_exp_f32_e32 v171, v112
	v_exp_f32_e32 v173, v113
	v_exp_f32_e32 v179, v114
	v_exp_f32_e32 v180, v115
	v_exp_f32_e32 v232, v116
	v_exp_f32_e32 v233, v117
	v_exp_f32_e32 v234, v118
	v_exp_f32_e32 v235, v119
	v_add_f32_e32 v190, v190, v171
	s_waitcnt lgkmcnt(5)
	v_mfma_f32_32x32x16_bf16 v[48:63], v[216:219], v[156:159], v[48:63]
	ds_read_b128 v[216:219], v187 offset:57344
	v_add_f32_e32 v191, v191, v173
	v_add_f32_e32 v190, v190, v179
	v_add_f32_e32 v191, v191, v180
	v_add_f32_e32 v190, v190, v232
	v_add_f32_e32 v191, v191, v233
	v_add_f32_e32 v190, v190, v234
	v_add_f32_e32 v191, v191, v235
	v_cvt_pk_bf16_f32 v152, v171, v173
	s_waitcnt lgkmcnt(5)
	v_mfma_f32_32x32x16_bf16 v[32:47], v[220:223], v[156:159], v[32:47]
	ds_read_b128 v[220:223], v187 offset:61440
	v_cvt_pk_bf16_f32 v153, v179, v180
	v_cvt_pk_bf16_f32 v154, v232, v233
	v_cvt_pk_bf16_f32 v155, v234, v235
	s_waitcnt lgkmcnt(5)
	v_mfma_f32_32x32x16_bf16 v[16:31], v[224:227], v[156:159], v[16:31]
	ds_read_b128 v[224:227], v188 offset:49152
	s_waitcnt lgkmcnt(5)
	v_mfma_f32_32x32x16_bf16 v[0:15], v[228:231], v[156:159], v[0:15]
	ds_read_b128 v[228:231], v188 offset:53248
	v_exp_f32_e32 v171, v120
	v_exp_f32_e32 v173, v121
	v_exp_f32_e32 v179, v122
	v_exp_f32_e32 v180, v123
	v_exp_f32_e32 v232, v124
	v_exp_f32_e32 v233, v125
	v_exp_f32_e32 v234, v126
	v_exp_f32_e32 v235, v127
	v_add_f32_e32 v190, v190, v171
	v_add_f32_e32 v191, v191, v173
	v_add_f32_e32 v190, v190, v179
	v_add_f32_e32 v191, v191, v180
	v_add_f32_e32 v190, v190, v232
	v_add_f32_e32 v191, v191, v233
	v_add_f32_e32 v190, v190, v234
	v_add_f32_e32 v191, v191, v235
	v_cvt_pk_bf16_f32 v156, v171, v173
	v_cvt_pk_bf16_f32 v157, v179, v180
	v_cvt_pk_bf16_f32 v158, v232, v233
	v_cvt_pk_bf16_f32 v159, v234, v235
	v_add_f32_e32 v190, v190, v191
	v_cmp_ngt_f32_e32 vcc, 0x71800000, v190
	s_nop 4
	s_cbranch_vccnz .Lattn_redo_T31
	v_add_f32_e32 v167, v167, v190

.Lattn_redo_L0:
	v_max3_f32 v254, v96, v97, v98
	v_max3_f32 v255, v112, v113, v114
	v_max3_f32 v254, v254, v99, v100
	v_max3_f32 v255, v255, v115, v116
	v_max3_f32 v254, v254, v101, v102
	v_max3_f32 v255, v255, v117, v118
	v_max3_f32 v254, v254, v103, v104
	v_max3_f32 v255, v255, v119, v120
	v_max3_f32 v254, v254, v105, v106
	v_max3_f32 v255, v255, v121, v122
	v_max3_f32 v254, v254, v107, v108
	v_max3_f32 v255, v255, v123, v124
	v_max3_f32 v254, v254, v109, v110
	v_max3_f32 v255, v255, v125, v126
	v_max3_f32 v254, v254, v111, v127
	v_max_f32_e32 v254, v254, v255
	v_mov_b32_e32 v255, v254
	s_nop 1
	v_permlane32_swap_b32_e32 v254, v255
	v_max_f32_e32 v254, v254, v255
	v_add_f32_e32 v180, 0x4138aa3b, v175
	v_cmp_gt_f32_e32 vcc, v254, v180
	s_nop 1
	v_cndmask_b32_e32 v180, v175, v254, vcc
	v_sub_f32_e32 v255, v175, v180
	v_exp_f32_e32 v174, v255
	v_mov_b32_e32 v175, v180
	v_sub_f32_e32 v96, v96, v175
	v_sub_f32_e32 v97, v97, v175
	v_sub_f32_e32 v98, v98, v175
	v_sub_f32_e32 v99, v99, v175
	v_sub_f32_e32 v100, v100, v175
	v_sub_f32_e32 v101, v101, v175
	v_sub_f32_e32 v102, v102, v175
	v_sub_f32_e32 v103, v103, v175
	v_exp_f32_e32 v96, v96
	v_exp_f32_e32 v97, v97
	v_exp_f32_e32 v98, v98
	v_exp_f32_e32 v99, v99
	v_exp_f32_e32 v100, v100
	v_exp_f32_e32 v101, v101
	v_exp_f32_e32 v102, v102
	v_exp_f32_e32 v103, v103
	v_add_f32_e32 v190, v96, v97
	v_add_f32_e32 v191, v98, v99
	v_add_f32_e32 v190, v190, v100
	v_add_f32_e32 v191, v191, v101
	v_add_f32_e32 v190, v190, v102
	v_add_f32_e32 v191, v191, v103
	v_cvt_pk_bf16_f32 v144, v96, v97
	v_cvt_pk_bf16_f32 v145, v98, v99
	v_cvt_pk_bf16_f32 v146, v100, v101
	v_cvt_pk_bf16_f32 v147, v102, v103
	v_sub_f32_e32 v104, v104, v175
	v_sub_f32_e32 v105, v105, v175
	v_sub_f32_e32 v106, v106, v175
	v_sub_f32_e32 v107, v107, v175
	v_sub_f32_e32 v108, v108, v175
	v_sub_f32_e32 v109, v109, v175
	v_sub_f32_e32 v110, v110, v175
	v_sub_f32_e32 v111, v111, v175
	v_exp_f32_e32 v104, v104
	v_exp_f32_e32 v105, v105
	v_exp_f32_e32 v106, v106
	v_exp_f32_e32 v107, v107
	v_exp_f32_e32 v108, v108
	v_exp_f32_e32 v109, v109
	v_exp_f32_e32 v110, v110
	v_exp_f32_e32 v111, v111
	v_add_f32_e32 v190, v190, v104
	v_add_f32_e32 v191, v191, v105
	v_add_f32_e32 v190, v190, v106
	v_add_f32_e32 v191, v191, v107
	v_add_f32_e32 v190, v190, v108
	v_add_f32_e32 v191, v191, v109
	v_add_f32_e32 v190, v190, v110
	v_add_f32_e32 v191, v191, v111
	v_cvt_pk_bf16_f32 v148, v104, v105
	v_cvt_pk_bf16_f32 v149, v106, v107
	v_cvt_pk_bf16_f32 v150, v108, v109
	v_cvt_pk_bf16_f32 v151, v110, v111
	v_sub_f32_e32 v112, v112, v175
	v_sub_f32_e32 v113, v113, v175
	v_sub_f32_e32 v114, v114, v175
	v_sub_f32_e32 v115, v115, v175
	v_sub_f32_e32 v116, v116, v175
	v_sub_f32_e32 v117, v117, v175
	v_sub_f32_e32 v118, v118, v175
	v_sub_f32_e32 v119, v119, v175
	v_exp_f32_e32 v112, v112
	v_exp_f32_e32 v113, v113
	v_exp_f32_e32 v114, v114
	v_exp_f32_e32 v115, v115
	v_exp_f32_e32 v116, v116
	v_exp_f32_e32 v117, v117
	v_exp_f32_e32 v118, v118
	v_exp_f32_e32 v119, v119
	v_add_f32_e32 v190, v190, v112
	v_add_f32_e32 v191, v191, v113
	v_add_f32_e32 v190, v190, v114
	v_add_f32_e32 v191, v191, v115
	v_add_f32_e32 v190, v190, v116
	v_add_f32_e32 v191, v191, v117
	v_add_f32_e32 v190, v190, v118
	v_add_f32_e32 v191, v191, v119
	v_cvt_pk_bf16_f32 v152, v112, v113
	v_cvt_pk_bf16_f32 v153, v114, v115
	v_cvt_pk_bf16_f32 v154, v116, v117
	v_cvt_pk_bf16_f32 v155, v118, v119
	v_sub_f32_e32 v120, v120, v175
	v_sub_f32_e32 v121, v121, v175
	v_sub_f32_e32 v122, v122, v175
	v_sub_f32_e32 v123, v123, v175
	v_sub_f32_e32 v124, v124, v175
	v_sub_f32_e32 v125, v125, v175
	v_sub_f32_e32 v126, v126, v175
	v_sub_f32_e32 v127, v127, v175
	v_exp_f32_e32 v120, v120
	v_exp_f32_e32 v121, v121
	v_exp_f32_e32 v122, v122
	v_exp_f32_e32 v123, v123
	v_exp_f32_e32 v124, v124
	v_exp_f32_e32 v125, v125
	v_exp_f32_e32 v126, v126
	v_exp_f32_e32 v127, v127
	v_add_f32_e32 v190, v190, v120
	v_add_f32_e32 v191, v191, v121
	v_add_f32_e32 v190, v190, v122
	v_add_f32_e32 v191, v191, v123
	v_add_f32_e32 v190, v190, v124
	v_add_f32_e32 v191, v191, v125
	v_add_f32_e32 v190, v190, v126
	v_add_f32_e32 v191, v191, v127
	v_cvt_pk_bf16_f32 v156, v120, v121
	v_cvt_pk_bf16_f32 v157, v122, v123
	v_cvt_pk_bf16_f32 v158, v124, v125
	v_cvt_pk_bf16_f32 v159, v126, v127
	v_add_f32_e32 v190, v190, v191
	v_fma_f32 v167, v167, v174, v190
	s_cbranch_vccz .Lattn_noresc_rL0
	s_nop 7
	s_nop 7
	v_pk_mul_f32 v[0:1], v[0:1], v[174:175] op_sel_hi:[1,0]
	v_pk_mul_f32 v[2:3], v[2:3], v[174:175] op_sel_hi:[1,0]
	v_pk_mul_f32 v[4:5], v[4:5], v[174:175] op_sel_hi:[1,0]
	v_pk_mul_f32 v[6:7], v[6:7], v[174:175] op_sel_hi:[1,0]
	v_pk_mul_f32 v[8:9], v[8:9], v[174:175] op_sel_hi:[1,0]
	v_pk_mul_f32 v[10:11], v[10:11], v[174:175] op_sel_hi:[1,0]
	v_pk_mul_f32 v[12:13], v[12:13], v[174:175] op_sel_hi:[1,0]
	v_pk_mul_f32 v[14:15], v[14:15], v[174:175] op_sel_hi:[1,0]
	v_pk_mul_f32 v[16:17], v[16:17], v[174:175] op_sel_hi:[1,0]
	v_pk_mul_f32 v[18:19], v[18:19], v[174:175] op_sel_hi:[1,0]
	v_pk_mul_f32 v[20:21], v[20:21], v[174:175] op_sel_hi:[1,0]
	v_pk_mul_f32 v[22:23], v[22:23], v[174:175] op_sel_hi:[1,0]
	v_pk_mul_f32 v[24:25], v[24:25], v[174:175] op_sel_hi:[1,0]
	v_pk_mul_f32 v[26:27], v[26:27], v[174:175] op_sel_hi:[1,0]
	v_pk_mul_f32 v[28:29], v[28:29], v[174:175] op_sel_hi:[1,0]
	v_pk_mul_f32 v[30:31], v[30:31], v[174:175] op_sel_hi:[1,0]
	v_pk_mul_f32 v[32:33], v[32:33], v[174:175] op_sel_hi:[1,0]
	v_pk_mul_f32 v[34:35], v[34:35], v[174:175] op_sel_hi:[1,0]
	v_pk_mul_f32 v[36:37], v[36:37], v[174:175] op_sel_hi:[1,0]
	v_pk_mul_f32 v[38:39], v[38:39], v[174:175] op_sel_hi:[1,0]
	v_pk_mul_f32 v[40:41], v[40:41], v[174:175] op_sel_hi:[1,0]
	v_pk_mul_f32 v[42:43], v[42:43], v[174:175] op_sel_hi:[1,0]
	v_pk_mul_f32 v[44:45], v[44:45], v[174:175] op_sel_hi:[1,0]
	v_pk_mul_f32 v[46:47], v[46:47], v[174:175] op_sel_hi:[1,0]
	v_pk_mul_f32 v[48:49], v[48:49], v[174:175] op_sel_hi:[1,0]
	v_pk_mul_f32 v[50:51], v[50:51], v[174:175] op_sel_hi:[1,0]
	v_pk_mul_f32 v[52:53], v[52:53], v[174:175] op_sel_hi:[1,0]
	v_pk_mul_f32 v[54:55], v[54:55], v[174:175] op_sel_hi:[1,0]
	v_pk_mul_f32 v[56:57], v[56:57], v[174:175] op_sel_hi:[1,0]
	v_pk_mul_f32 v[58:59], v[58:59], v[174:175] op_sel_hi:[1,0]
	v_pk_mul_f32 v[60:61], v[60:61], v[174:175] op_sel_hi:[1,0]
	v_pk_mul_f32 v[62:63], v[62:63], v[174:175] op_sel_hi:[1,0]
	s_nop 1

.Lattn_redo_L1:
	v_max3_f32 v254, v64, v65, v66
	v_max3_f32 v255, v80, v81, v82
	v_max3_f32 v254, v254, v67, v68
	v_max3_f32 v255, v255, v83, v84
	v_max3_f32 v254, v254, v69, v70
	v_max3_f32 v255, v255, v85, v86
	v_max3_f32 v254, v254, v71, v72
	v_max3_f32 v255, v255, v87, v88
	v_max3_f32 v254, v254, v73, v74
	v_max3_f32 v255, v255, v89, v90
	v_max3_f32 v254, v254, v75, v76
	v_max3_f32 v255, v255, v91, v92
	v_max3_f32 v254, v254, v77, v78
	v_max3_f32 v255, v255, v93, v94
	v_max3_f32 v254, v254, v79, v95
	v_max_f32_e32 v254, v254, v255
	v_mov_b32_e32 v255, v254
	s_nop 1
	v_permlane32_swap_b32_e32 v254, v255
	v_max_f32_e32 v254, v254, v255
	v_add_f32_e32 v180, 0x4138aa3b, v175
	v_cmp_gt_f32_e32 vcc, v254, v180
	s_nop 1
	v_cndmask_b32_e32 v180, v175, v254, vcc
	v_sub_f32_e32 v255, v175, v180
	v_exp_f32_e32 v174, v255
	v_mov_b32_e32 v175, v180
	v_sub_f32_e32 v64, v64, v175
	v_sub_f32_e32 v65, v65, v175
	v_sub_f32_e32 v66, v66, v175
	v_sub_f32_e32 v67, v67, v175
	v_sub_f32_e32 v68, v68, v175
	v_sub_f32_e32 v69, v69, v175
	v_sub_f32_e32 v70, v70, v175
	v_sub_f32_e32 v71, v71, v175
	v_exp_f32_e32 v64, v64
	v_exp_f32_e32 v65, v65
	v_exp_f32_e32 v66, v66
	v_exp_f32_e32 v67, v67
	v_exp_f32_e32 v68, v68
	v_exp_f32_e32 v69, v69
	v_exp_f32_e32 v70, v70
	v_exp_f32_e32 v71, v71
	v_add_f32_e32 v190, v64, v65
	v_add_f32_e32 v191, v66, v67
	v_add_f32_e32 v190, v190, v68
	v_add_f32_e32 v191, v191, v69
	v_add_f32_e32 v190, v190, v70
	v_add_f32_e32 v191, v191, v71
	v_cvt_pk_bf16_f32 v144, v64, v65
	v_cvt_pk_bf16_f32 v145, v66, v67
	v_cvt_pk_bf16_f32 v146, v68, v69
	v_cvt_pk_bf16_f32 v147, v70, v71
	v_sub_f32_e32 v72, v72, v175
	v_sub_f32_e32 v73, v73, v175
	v_sub_f32_e32 v74, v74, v175
	v_sub_f32_e32 v75, v75, v175
	v_sub_f32_e32 v76, v76, v175
	v_sub_f32_e32 v77, v77, v175
	v_sub_f32_e32 v78, v78, v175
	v_sub_f32_e32 v79, v79, v175
	v_exp_f32_e32 v72, v72
	v_exp_f32_e32 v73, v73
	v_exp_f32_e32 v74, v74
	v_exp_f32_e32 v75, v75
	v_exp_f32_e32 v76, v76
	v_exp_f32_e32 v77, v77
	v_exp_f32_e32 v78, v78
	v_exp_f32_e32 v79, v79
	v_add_f32_e32 v190, v190, v72
	v_add_f32_e32 v191, v191, v73
	v_add_f32_e32 v190, v190, v74
	v_add_f32_e32 v191, v191, v75
	v_add_f32_e32 v190, v190, v76
	v_add_f32_e32 v191, v191, v77
	v_add_f32_e32 v190, v190, v78
	v_add_f32_e32 v191, v191, v79
	v_cvt_pk_bf16_f32 v148, v72, v73
	v_cvt_pk_bf16_f32 v149, v74, v75
	v_cvt_pk_bf16_f32 v150, v76, v77
	v_cvt_pk_bf16_f32 v151, v78, v79
	v_sub_f32_e32 v80, v80, v175
	v_sub_f32_e32 v81, v81, v175
	v_sub_f32_e32 v82, v82, v175
	v_sub_f32_e32 v83, v83, v175
	v_sub_f32_e32 v84, v84, v175
	v_sub_f32_e32 v85, v85, v175
	v_sub_f32_e32 v86, v86, v175
	v_sub_f32_e32 v87, v87, v175
	v_exp_f32_e32 v80, v80
	v_exp_f32_e32 v81, v81
	v_exp_f32_e32 v82, v82
	v_exp_f32_e32 v83, v83
	v_exp_f32_e32 v84, v84
	v_exp_f32_e32 v85, v85
	v_exp_f32_e32 v86, v86
	v_exp_f32_e32 v87, v87
	v_add_f32_e32 v190, v190, v80
	v_add_f32_e32 v191, v191, v81
	v_add_f32_e32 v190, v190, v82
	v_add_f32_e32 v191, v191, v83
	v_add_f32_e32 v190, v190, v84
	v_add_f32_e32 v191, v191, v85
	v_add_f32_e32 v190, v190, v86
	v_add_f32_e32 v191, v191, v87
	v_cvt_pk_bf16_f32 v152, v80, v81
	v_cvt_pk_bf16_f32 v153, v82, v83
	v_cvt_pk_bf16_f32 v154, v84, v85
	v_cvt_pk_bf16_f32 v155, v86, v87
	v_sub_f32_e32 v88, v88, v175
	v_sub_f32_e32 v89, v89, v175
	v_sub_f32_e32 v90, v90, v175
	v_sub_f32_e32 v91, v91, v175
	v_sub_f32_e32 v92, v92, v175
	v_sub_f32_e32 v93, v93, v175
	v_sub_f32_e32 v94, v94, v175
	v_sub_f32_e32 v95, v95, v175
	v_exp_f32_e32 v88, v88
	v_exp_f32_e32 v89, v89
	v_exp_f32_e32 v90, v90
	v_exp_f32_e32 v91, v91
	v_exp_f32_e32 v92, v92
	v_exp_f32_e32 v93, v93
	v_exp_f32_e32 v94, v94
	v_exp_f32_e32 v95, v95
	v_add_f32_e32 v190, v190, v88
	v_add_f32_e32 v191, v191, v89
	v_add_f32_e32 v190, v190, v90
	v_add_f32_e32 v191, v191, v91
	v_add_f32_e32 v190, v190, v92
	v_add_f32_e32 v191, v191, v93
	v_add_f32_e32 v190, v190, v94
	v_add_f32_e32 v191, v191, v95
	v_cvt_pk_bf16_f32 v156, v88, v89
	v_cvt_pk_bf16_f32 v157, v90, v91
	v_cvt_pk_bf16_f32 v158, v92, v93
	v_cvt_pk_bf16_f32 v159, v94, v95
	v_add_f32_e32 v190, v190, v191
	v_fma_f32 v167, v167, v174, v190
	s_cbranch_vccz .Lattn_noresc_rL1
	s_nop 7
	s_nop 7
	v_pk_mul_f32 v[0:1], v[0:1], v[174:175] op_sel_hi:[1,0]
	v_pk_mul_f32 v[2:3], v[2:3], v[174:175] op_sel_hi:[1,0]
	v_pk_mul_f32 v[4:5], v[4:5], v[174:175] op_sel_hi:[1,0]
	v_pk_mul_f32 v[6:7], v[6:7], v[174:175] op_sel_hi:[1,0]
	v_pk_mul_f32 v[8:9], v[8:9], v[174:175] op_sel_hi:[1,0]
	v_pk_mul_f32 v[10:11], v[10:11], v[174:175] op_sel_hi:[1,0]
	v_pk_mul_f32 v[12:13], v[12:13], v[174:175] op_sel_hi:[1,0]
	v_pk_mul_f32 v[14:15], v[14:15], v[174:175] op_sel_hi:[1,0]
	v_pk_mul_f32 v[16:17], v[16:17], v[174:175] op_sel_hi:[1,0]
	v_pk_mul_f32 v[18:19], v[18:19], v[174:175] op_sel_hi:[1,0]
	v_pk_mul_f32 v[20:21], v[20:21], v[174:175] op_sel_hi:[1,0]
	v_pk_mul_f32 v[22:23], v[22:23], v[174:175] op_sel_hi:[1,0]
	v_pk_mul_f32 v[24:25], v[24:25], v[174:175] op_sel_hi:[1,0]
	v_pk_mul_f32 v[26:27], v[26:27], v[174:175] op_sel_hi:[1,0]
	v_pk_mul_f32 v[28:29], v[28:29], v[174:175] op_sel_hi:[1,0]
	v_pk_mul_f32 v[30:31], v[30:31], v[174:175] op_sel_hi:[1,0]
	v_pk_mul_f32 v[32:33], v[32:33], v[174:175] op_sel_hi:[1,0]
	v_pk_mul_f32 v[34:35], v[34:35], v[174:175] op_sel_hi:[1,0]
	v_pk_mul_f32 v[36:37], v[36:37], v[174:175] op_sel_hi:[1,0]
	v_pk_mul_f32 v[38:39], v[38:39], v[174:175] op_sel_hi:[1,0]
	v_pk_mul_f32 v[40:41], v[40:41], v[174:175] op_sel_hi:[1,0]
	v_pk_mul_f32 v[42:43], v[42:43], v[174:175] op_sel_hi:[1,0]
	v_pk_mul_f32 v[44:45], v[44:45], v[174:175] op_sel_hi:[1,0]
	v_pk_mul_f32 v[46:47], v[46:47], v[174:175] op_sel_hi:[1,0]
	v_pk_mul_f32 v[48:49], v[48:49], v[174:175] op_sel_hi:[1,0]
	v_pk_mul_f32 v[50:51], v[50:51], v[174:175] op_sel_hi:[1,0]
	v_pk_mul_f32 v[52:53], v[52:53], v[174:175] op_sel_hi:[1,0]
	v_pk_mul_f32 v[54:55], v[54:55], v[174:175] op_sel_hi:[1,0]
	v_pk_mul_f32 v[56:57], v[56:57], v[174:175] op_sel_hi:[1,0]
	v_pk_mul_f32 v[58:59], v[58:59], v[174:175] op_sel_hi:[1,0]
	v_pk_mul_f32 v[60:61], v[60:61], v[174:175] op_sel_hi:[1,0]
	v_pk_mul_f32 v[62:63], v[62:63], v[174:175] op_sel_hi:[1,0]
	s_nop 1

.Lattn_top_t0:
	s_waitcnt lgkmcnt(5)
	v_mfma_f32_32x32x16_bf16 v[96:111], v[208:211], v[128:131], 0
	ds_read_b128 v[208:211], v185 offset:16384
	s_add_i32 s2, s42, 3
	v_max3_f32 v254, v64, v65, v66
	s_and_b32 s2, s2, 31
	v_max3_f32 v255, v80, v81, v82
	s_mul_i32 s2, s2, 0x44000
	v_max3_f32 v254, v254, v67, v68
	s_add_i32 m0, s5, 49152
	v_max3_f32 v255, v255, v83, v84
	s_waitcnt lgkmcnt(5)
	v_mfma_f32_32x32x16_bf16 v[112:127], v[212:215], v[128:131], 0
	ds_read_b128 v[212:215], v185 offset:20480
	s_add_u32 s40, s26, s2
	v_max3_f32 v254, v254, v69, v70
	s_addc_u32 s41, s27, 0
	v_max3_f32 v255, v255, v85, v86
	global_load_lds_dwordx4 v170, s[40:41]
	v_max3_f32 v254, v254, v71, v72
	s_add_i32 m0, s5, 57344
	v_max3_f32 v255, v255, v87, v88
	s_waitcnt lgkmcnt(5)
	v_mfma_f32_32x32x16_bf16 v[96:111], v[216:219], v[132:135], v[96:111]
	ds_read_b128 v[216:219], v187 offset:0
	s_add_u32 s40, s40, 0x80
	v_max3_f32 v254, v254, v73, v74
	s_addc_u32 s41, s41, 0
	v_max3_f32 v255, v255, v89, v90
	global_load_lds_dwordx4 v170, s[40:41]
	v_max3_f32 v254, v254, v75, v76
	s_add_i32 s2, s42, 2
	v_max3_f32 v255, v255, v91, v92
	s_waitcnt lgkmcnt(5)
	v_mfma_f32_32x32x16_bf16 v[112:127], v[220:223], v[132:135], v[112:127]
	ds_read_b128 v[220:223], v187 offset:4096
	s_and_b32 s2, s2, 31
	v_max3_f32 v254, v254, v77, v78
	s_lshl_b32 s2, s2, 7
	v_max3_f32 v255, v255, v93, v94
	s_add_i32 m0, s5, 98304
	v_max3_f32 v254, v254, v79, v95
	s_add_u32 s44, s10, s2
	v_max_f32_e32 v254, v254, v255
	s_waitcnt lgkmcnt(5)
	v_mfma_f32_32x32x16_bf16 v[96:111], v[224:227], v[136:139], v[96:111]
	ds_read_b128 v[224:227], v187 offset:8192
	v_mov_b32_e32 v180, 0xc2800000
	v_cmp_lt_f32_e32 vcc, 0x4138aa3b, v254
	v_cmp_gt_f32_e64 s[40:41], v180, v254
	s_addc_u32 s45, s11, 0
	global_load_lds_dwordx4 v172, s[44:45]
	s_add_i32 m0, s5, 106496
	s_add_u32 s44, s44, 0x204000
	s_addc_u32 s45, s45, 0
	s_waitcnt lgkmcnt(5)
	v_mfma_f32_32x32x16_bf16 v[112:127], v[228:231], v[136:139], v[112:127]
	ds_read_b128 v[228:231], v187 offset:12288
	global_load_lds_dwordx4 v172, s[44:45]
	s_or_b64 vcc, vcc, s[40:41]
	s_nop 0

.Lattn_loop_s:
.Lattn_top_L0:
	s_waitcnt vmcnt(4)
	s_barrier
	s_waitcnt lgkmcnt(5)
	v_mfma_f32_32x32x16_bf16 v[48:63], v[216:219], v[144:147], v[48:63]
	ds_read_b128 v[216:219], v188 offset:8192
	s_add_i32 s2, s42, 3
	v_max3_f32 v254, v96, v97, v98
	s_and_b32 s2, s2, 31
	v_max3_f32 v255, v112, v113, v114
	s_mul_i32 s2, s2, 0x44000
	v_max3_f32 v254, v254, v99, v100
	s_add_i32 m0, s5, 0
	v_max3_f32 v255, v255, v115, v116
	s_waitcnt lgkmcnt(5)
	v_mfma_f32_32x32x16_bf16 v[32:47], v[220:223], v[144:147], v[32:47]
	ds_read_b128 v[220:223], v188 offset:12288
	s_add_u32 s40, s26, s2
	v_max3_f32 v254, v254, v101, v102
	s_addc_u32 s41, s27, 0
	v_max3_f32 v255, v255, v117, v118
	global_load_lds_dwordx4 v170, s[40:41]
	v_max3_f32 v254, v254, v103, v104
	s_add_i32 m0, s5, 8192
	v_max3_f32 v255, v255, v119, v120
	s_waitcnt lgkmcnt(5)
	v_mfma_f32_32x32x16_bf16 v[16:31], v[224:227], v[144:147], v[16:31]
	ds_read_b128 v[224:227], v186 offset:0
	s_add_u32 s40, s40, 0x80
	v_max3_f32 v254, v254, v105, v106
	s_addc_u32 s41, s41, 0
	v_max3_f32 v255, v255, v121, v122
	global_load_lds_dwordx4 v170, s[40:41]
	v_max3_f32 v254, v254, v107, v108
	s_add_i32 s2, s42, 2
	v_max3_f32 v255, v255, v123, v124
	s_waitcnt lgkmcnt(5)
	v_mfma_f32_32x32x16_bf16 v[0:15], v[228:231], v[144:147], v[0:15]
	ds_read_b128 v[228:231], v186 offset:4096
	s_and_b32 s2, s2, 31
	v_max3_f32 v254, v254, v109, v110
	s_lshl_b32 s2, s2, 7
	v_max3_f32 v255, v255, v125, v126
	s_add_i32 m0, s5, 114688
	v_max3_f32 v254, v254, v111, v127
	s_add_u32 s44, s10, s2
	v_max_f32_e32 v254, v254, v255
	s_waitcnt lgkmcnt(5)
	v_mfma_f32_32x32x16_bf16 v[48:63], v[208:211], v[148:151], v[48:63]
	ds_read_b128 v[208:211], v186 offset:8192
	v_cmp_lt_f32_e32 vcc, 0x4138aa3b, v254
	s_addc_u32 s45, s11, 0
	global_load_lds_dwordx4 v172, s[44:45]
	s_add_i32 m0, s5, 122880
	s_add_u32 s44, s44, 0x204000
	s_addc_u32 s45, s45, 0
	global_load_lds_dwordx4 v172, s[44:45]

.Lattn_noresc_L0:
.Lattn_top_L1:
	s_waitcnt vmcnt(4)
	s_barrier
	s_waitcnt lgkmcnt(5)
	v_mfma_f32_32x32x16_bf16 v[48:63], v[216:219], v[144:147], v[48:63]
	ds_read_b128 v[216:219], v188 offset:24576
	s_add_i32 s2, s42, 4
	v_max3_f32 v254, v64, v65, v66
	s_and_b32 s2, s2, 31
	v_max3_f32 v255, v80, v81, v82
	s_mul_i32 s2, s2, 0x44000
	v_max3_f32 v254, v254, v67, v68
	s_add_i32 m0, s5, 16384
	v_max3_f32 v255, v255, v83, v84
	s_waitcnt lgkmcnt(5)
	v_mfma_f32_32x32x16_bf16 v[32:47], v[220:223], v[144:147], v[32:47]
	ds_read_b128 v[220:223], v188 offset:28672
	s_add_u32 s40, s26, s2
	v_max3_f32 v254, v254, v69, v70
	s_addc_u32 s41, s27, 0
	v_max3_f32 v255, v255, v85, v86
	global_load_lds_dwordx4 v170, s[40:41]
	v_max3_f32 v254, v254, v71, v72
	s_add_i32 m0, s5, 24576
	v_max3_f32 v255, v255, v87, v88
	s_waitcnt lgkmcnt(5)
	v_mfma_f32_32x32x16_bf16 v[16:31], v[224:227], v[144:147], v[16:31]
	ds_read_b128 v[224:227], v186 offset:16384
	s_add_u32 s40, s40, 0x80
	v_max3_f32 v254, v254, v73, v74
	s_addc_u32 s41, s41, 0
	v_max3_f32 v255, v255, v89, v90
	global_load_lds_dwordx4 v170, s[40:41]
	v_max3_f32 v254, v254, v75, v76
	s_add_i32 s2, s42, 3
	v_max3_f32 v255, v255, v91, v92
	s_waitcnt lgkmcnt(5)
	v_mfma_f32_32x32x16_bf16 v[0:15], v[228:231], v[144:147], v[0:15]
	ds_read_b128 v[228:231], v186 offset:20480
	s_and_b32 s2, s2, 31
	v_max3_f32 v254, v254, v77, v78
	s_lshl_b32 s2, s2, 7
	v_max3_f32 v255, v255, v93, v94
	s_add_i32 m0, s5, 65536
	v_max3_f32 v254, v254, v79, v95
	s_add_u32 s44, s10, s2
	v_max_f32_e32 v254, v254, v255
	s_waitcnt lgkmcnt(5)
	v_mfma_f32_32x32x16_bf16 v[48:63], v[208:211], v[148:151], v[48:63]
	ds_read_b128 v[208:211], v186 offset:24576
	v_cmp_lt_f32_e32 vcc, 0x4138aa3b, v254
	s_addc_u32 s45, s11, 0
	global_load_lds_dwordx4 v172, s[44:45]
	s_add_i32 m0, s5, 73728
	s_add_u32 s44, s44, 0x204000
	s_addc_u32 s45, s45, 0
	global_load_lds_dwordx4 v172, s[44:45]

.Lattn_noresc_L1:
.Lattn_top_L2:
	s_waitcnt vmcnt(4)
	s_barrier
	s_waitcnt lgkmcnt(5)
	v_mfma_f32_32x32x16_bf16 v[48:63], v[216:219], v[144:147], v[48:63]
	ds_read_b128 v[216:219], v188 offset:40960
	s_add_i32 s2, s42, 5
	v_max3_f32 v254, v96, v97, v98
	s_and_b32 s2, s2, 31
	v_max3_f32 v255, v112, v113, v114
	s_mul_i32 s2, s2, 0x44000
	v_max3_f32 v254, v254, v99, v100
	s_add_i32 m0, s5, 32768
	v_max3_f32 v255, v255, v115, v116
	s_waitcnt lgkmcnt(5)
	v_mfma_f32_32x32x16_bf16 v[32:47], v[220:223], v[144:147], v[32:47]
	ds_read_b128 v[220:223], v188 offset:45056
	s_add_u32 s40, s26, s2
	v_max3_f32 v254, v254, v101, v102
	s_addc_u32 s41, s27, 0
	v_max3_f32 v255, v255, v117, v118
	global_load_lds_dwordx4 v170, s[40:41]
	v_max3_f32 v254, v254, v103, v104
	s_add_i32 m0, s5, 40960
	v_max3_f32 v255, v255, v119, v120
	s_waitcnt lgkmcnt(5)
	v_mfma_f32_32x32x16_bf16 v[16:31], v[224:227], v[144:147], v[16:31]
	ds_read_b128 v[224:227], v186 offset:32768
	s_add_u32 s40, s40, 0x80
	v_max3_f32 v254, v254, v105, v106
	s_addc_u32 s41, s41, 0
	v_max3_f32 v255, v255, v121, v122
	global_load_lds_dwordx4 v170, s[40:41]
	v_max3_f32 v254, v254, v107, v108
	s_add_i32 s2, s42, 4
	v_max3_f32 v255, v255, v123, v124
	s_waitcnt lgkmcnt(5)
	v_mfma_f32_32x32x16_bf16 v[0:15], v[228:231], v[144:147], v[0:15]
	ds_read_b128 v[228:231], v186 offset:36864
	s_and_b32 s2, s2, 31
	v_max3_f32 v254, v254, v109, v110
	s_lshl_b32 s2, s2, 7
	v_max3_f32 v255, v255, v125, v126
	s_add_i32 m0, s5, 81920
	v_max3_f32 v254, v254, v111, v127
	s_add_u32 s44, s10, s2
	v_max_f32_e32 v254, v254, v255
	s_waitcnt lgkmcnt(5)
	v_mfma_f32_32x32x16_bf16 v[48:63], v[208:211], v[148:151], v[48:63]
	ds_read_b128 v[208:211], v186 offset:40960
	v_cmp_lt_f32_e32 vcc, 0x4138aa3b, v254
	s_addc_u32 s45, s11, 0
	global_load_lds_dwordx4 v172, s[44:45]
	s_add_i32 m0, s5, 90112
	s_add_u32 s44, s44, 0x204000
	s_addc_u32 s45, s45, 0
	global_load_lds_dwordx4 v172, s[44:45]

.Lattn_noresc_L2:
.Lattn_top_L3:
	s_waitcnt vmcnt(4)
	s_barrier
	s_waitcnt lgkmcnt(5)
	v_mfma_f32_32x32x16_bf16 v[48:63], v[216:219], v[144:147], v[48:63]
	ds_read_b128 v[216:219], v188 offset:57344
	s_add_i32 s2, s42, 6
	v_max3_f32 v254, v64, v65, v66
	s_and_b32 s2, s2, 31
	v_max3_f32 v255, v80, v81, v82
	s_mul_i32 s2, s2, 0x44000
	v_max3_f32 v254, v254, v67, v68
	s_add_i32 m0, s5, 49152
	v_max3_f32 v255, v255, v83, v84
	s_waitcnt lgkmcnt(5)
	v_mfma_f32_32x32x16_bf16 v[32:47], v[220:223], v[144:147], v[32:47]
	ds_read_b128 v[220:223], v188 offset:61440
	s_add_u32 s40, s26, s2
	v_max3_f32 v254, v254, v69, v70
	s_addc_u32 s41, s27, 0
	v_max3_f32 v255, v255, v85, v86
	global_load_lds_dwordx4 v170, s[40:41]
	v_max3_f32 v254, v254, v71, v72
	s_add_i32 m0, s5, 57344
	v_max3_f32 v255, v255, v87, v88
	s_waitcnt lgkmcnt(5)
	v_mfma_f32_32x32x16_bf16 v[16:31], v[224:227], v[144:147], v[16:31]
	ds_read_b128 v[224:227], v186 offset:49152
	s_add_u32 s40, s40, 0x80
	v_max3_f32 v254, v254, v73, v74
	s_addc_u32 s41, s41, 0
	v_max3_f32 v255, v255, v89, v90
	global_load_lds_dwordx4 v170, s[40:41]
	v_max3_f32 v254, v254, v75, v76
	s_add_i32 s2, s42, 5
	v_max3_f32 v255, v255, v91, v92
	s_waitcnt lgkmcnt(5)
	v_mfma_f32_32x32x16_bf16 v[0:15], v[228:231], v[144:147], v[0:15]
	ds_read_b128 v[228:231], v186 offset:53248
	s_and_b32 s2, s2, 31
	v_max3_f32 v254, v254, v77, v78
	s_lshl_b32 s2, s2, 7
	v_max3_f32 v255, v255, v93, v94
	s_add_i32 m0, s5, 98304
	v_max3_f32 v254, v254, v79, v95
	s_add_u32 s44, s10, s2
	v_max_f32_e32 v254, v254, v255
	s_waitcnt lgkmcnt(5)
	v_mfma_f32_32x32x16_bf16 v[48:63], v[208:211], v[148:151], v[48:63]
	ds_read_b128 v[208:211], v186 offset:57344
	v_cmp_lt_f32_e32 vcc, 0x4138aa3b, v254
	s_addc_u32 s45, s11, 0
	global_load_lds_dwordx4 v172, s[44:45]
	s_add_i32 m0, s5, 106496
	s_add_u32 s44, s44, 0x204000
	s_addc_u32 s45, s45, 0
	global_load_lds_dwordx4 v172, s[44:45]

.Lattn_noresc_L3:
.Lattn_tripend_s:
	s_add_i32 s42, s42, 4
	s_add_i32 s47, s47, -1
	s_cmp_lg_u32 s47, 0
	s_cbranch_scc1 .Lattn_loop_s
.Lattn_top_T29:
	s_waitcnt vmcnt(4)
	s_barrier
	s_waitcnt lgkmcnt(5)
	v_mfma_f32_32x32x16_bf16 v[48:63], v[216:219], v[144:147], v[48:63]
	ds_read_b128 v[216:219], v188 offset:8192
	s_nop 3
	s_add_i32 s2, s42, 2
	v_max3_f32 v254, v96, v97, v98
	s_and_b32 s2, s2, 31
	v_max3_f32 v255, v112, v113, v114
	s_lshl_b32 s2, s2, 7
	v_max3_f32 v254, v254, v99, v100
	s_add_i32 m0, s5, 114688
	s_waitcnt lgkmcnt(5)
	v_mfma_f32_32x32x16_bf16 v[32:47], v[220:223], v[144:147], v[32:47]
	ds_read_b128 v[220:223], v188 offset:12288
	v_max3_f32 v255, v255, v115, v116
	s_add_u32 s44, s10, s2
	v_max3_f32 v254, v254, v101, v102
	v_max3_f32 v255, v255, v117, v118
	v_max3_f32 v254, v254, v103, v104
	v_max3_f32 v255, v255, v119, v120
	v_max3_f32 v254, v254, v105, v106
	v_max3_f32 v255, v255, v121, v122
	s_waitcnt lgkmcnt(5)
	v_mfma_f32_32x32x16_bf16 v[16:31], v[224:227], v[144:147], v[16:31]
	ds_read_b128 v[224:227], v186 offset:0
	v_max3_f32 v254, v254, v107, v108
	v_max3_f32 v255, v255, v123, v124
	v_max3_f32 v254, v254, v109, v110
	v_max3_f32 v255, v255, v125, v126
	v_max3_f32 v254, v254, v111, v127
	v_max_f32_e32 v254, v254, v255
	v_cmp_lt_f32_e32 vcc, 0x4138aa3b, v254
	s_addc_u32 s45, s11, 0
	s_waitcnt lgkmcnt(5)
	v_mfma_f32_32x32x16_bf16 v[0:15], v[228:231], v[144:147], v[0:15]
	ds_read_b128 v[228:231], v186 offset:4096
	global_load_lds_dwordx4 v172, s[44:45]
	s_add_i32 m0, s5, 122880
	s_add_u32 s44, s44, 0x204000
	s_addc_u32 s45, s45, 0
	global_load_lds_dwordx4 v172, s[44:45]

.Lattn_noresc_T29:
.Lattn_top_T30:
	s_waitcnt vmcnt(2)
	s_barrier
	s_waitcnt lgkmcnt(5)
	v_mfma_f32_32x32x16_bf16 v[48:63], v[216:219], v[144:147], v[48:63]
	ds_read_b128 v[216:219], v188 offset:24576
	s_nop 3
	v_max3_f32 v254, v64, v65, v66
	v_max3_f32 v255, v80, v81, v82
	v_max3_f32 v254, v254, v67, v68
	v_max3_f32 v255, v255, v83, v84
	v_max3_f32 v254, v254, v69, v70
	v_max3_f32 v255, v255, v85, v86
	v_max3_f32 v254, v254, v71, v72
	s_waitcnt lgkmcnt(5)
	v_mfma_f32_32x32x16_bf16 v[32:47], v[220:223], v[144:147], v[32:47]
	ds_read_b128 v[220:223], v188 offset:28672
	v_max3_f32 v255, v255, v87, v88
	v_max3_f32 v254, v254, v73, v74
	v_max3_f32 v255, v255, v89, v90
	v_max3_f32 v254, v254, v75, v76
	v_max3_f32 v255, v255, v91, v92
	v_max3_f32 v254, v254, v77, v78
	v_max3_f32 v255, v255, v93, v94
	v_max3_f32 v254, v254, v79, v95
	s_waitcnt lgkmcnt(5)
	v_mfma_f32_32x32x16_bf16 v[16:31], v[224:227], v[144:147], v[16:31]
	ds_read_b128 v[224:227], v186 offset:16384
	v_max_f32_e32 v254, v254, v255
	v_cmp_lt_f32_e32 vcc, 0x4138aa3b, v254
	s_nop 4

.Lattn_noresc_T30:
.Lattn_top_T31:
	s_waitcnt vmcnt(0)
	s_barrier
	s_waitcnt lgkmcnt(5)
	v_mfma_f32_32x32x16_bf16 v[48:63], v[216:219], v[144:147], v[48:63]
	ds_read_b128 v[216:219], v188 offset:40960
	s_nop 3
	v_max3_f32 v254, v96, v97, v98
	v_max3_f32 v255, v112, v113, v114
	v_max3_f32 v254, v254, v99, v100
	v_max3_f32 v255, v255, v115, v116
	v_max3_f32 v254, v254, v101, v102
	v_max3_f32 v255, v255, v117, v118
	v_max3_f32 v254, v254, v103, v104
	s_waitcnt lgkmcnt(5)
	v_mfma_f32_32x32x16_bf16 v[32:47], v[220:223], v[144:147], v[32:47]
	ds_read_b128 v[220:223], v188 offset:45056
	v_max3_f32 v255, v255, v119, v120
	v_max3_f32 v254, v254, v105, v106
	v_max3_f32 v255, v255, v121, v122
	v_max3_f32 v254, v254, v107, v108
	v_max3_f32 v255, v255, v123, v124
	v_max3_f32 v254, v254, v109, v110
	v_max3_f32 v255, v255, v125, v126
	v_max3_f32 v254, v254, v111, v127
	s_waitcnt lgkmcnt(5)
	v_mfma_f32_32x32x16_bf16 v[16:31], v[224:227], v[144:147], v[16:31]
	ds_read_b128 v[224:227], v186 offset:32768
	v_max_f32_e32 v254, v254, v255
	v_cmp_lt_f32_e32 vcc, 0x4138aa3b, v254
	s_nop 4
